# all four QK blocks rescheduled with deeper K prefetch; epilogue subln_g loads hoisted and waits dropped; hot-loop code placement tuned (nop padding)
# speedup vs baseline: 1.0008x; 1.0008x over previous
; __device__ __forceinline__ float bflo(unsigned w) { return __uint_as_float(w << 16); }
; __device__ __forceinline__ float bfhi(unsigned w) { return __uint_as_float(w & 0xffff0000u); }
; __device__ __forceinline__ float silu(float z) { return z * __builtin_amdgcn_rcpf(1.f + __builtin_amdgcn_exp2f(-1.4426950408889634f * z)); }
; template <bool SH> __device__ __forceinline__ void attn_unit(bf16_t* __restrict__ proj, int tok0, int kv0, int seq, int h, float lam, float oscale, const float* __restrict__ subg, char* lds, bool dry) {
;     ...
;     const int row = tid >> 2, dq = tid & 3, rl = row & 31, w = row >> 5, hh = (rl >> 2) & 1, r = (rl & 3) + 4 * (rl >> 3);
;     const float* xb = X + (w * 64 + dq * 16 + r) * 64 + hh * 32;
;     f32x4 a[8]; float ss = 0.f;
; #pragma unroll
;     for (int i = 0; i < 8; ++i) { a[i] = *(const f32x4*)(xb + i * 4); ss += a[i][0] * a[i][0] + a[i][1] * a[i][1] + a[i][2] * a[i][2] + a[i][3] * a[i][3]; }
;     ss += __shfl_xor(ss, 1); ss += __shfl_xor(ss, 2);
;     const float rn = __builtin_amdgcn_rsqf(ss * (1.f / 128.f) + 1e-5f) * oscale;
;     const float* gg = subg + dq * 32;
; #pragma unroll
;     for (int i = 0; i < 4; ++i) {
;       const u32x4 z = zg[i];
;       const f32x4 a0 = a[2 * i], a1 = a[2 * i + 1]; const f32x4 g0 = *(const f32x4*)(gg + i * 8), g1 = *(const f32x4*)(gg + i * 8 + 4);
;       u32x4 wv;
;       wv.x = cvtpk(a0[0] * rn * g0[0] * silu(bflo(z.x)), a0[1] * rn * g0[1] * silu(bfhi(z.x)));
;       wv.y = cvtpk(a0[2] * rn * g0[2] * silu(bflo(z.y)), a0[3] * rn * g0[3] * silu(bfhi(z.y)));
;       wv.z = cvtpk(a1[0] * rn * g1[0] * silu(bflo(z.z)), a1[1] * rn * g1[1] * silu(bfhi(z.z)));
;       wv.w = cvtpk(a1[2] * rn * g1[2] * silu(bflo(z.w)), a1[3] * rn * g1[3] * silu(bfhi(z.w)));
.LBB0_297:
	v_lshlrev_b32_e32 v211, 7, v202
	global_load_dwordx4 v[212:215], v211, s[22:23]
	global_load_dwordx4 v[216:219], v211, s[22:23] offset:16
	global_load_dwordx4 v[220:223], v211, s[22:23] offset:32
	global_load_dwordx4 v[224:227], v211, s[22:23] offset:48
	global_load_dwordx4 v[228:231], v211, s[22:23] offset:64
	global_load_dwordx4 v[232:235], v211, s[22:23] offset:80
	global_load_dwordx4 v[236:239], v211, s[22:23] offset:96
	global_load_dwordx4 v[240:243], v211, s[22:23] offset:112
	v_lshrrev_b32_e32 v1, 1, v183
	v_lshrrev_b32_e32 v2, 1, v182
	v_lshlrev_b32_e32 v3, 4, v202
	s_mov_b32 s0, 0xffffc0
	v_bfe_u32 v0, v182, 2, 2
	v_and_b32_e32 v1, 12, v1
	v_and_or_b32 v2, v2, s0, v3
	v_or3_b32 v0, v0, v1, v2
	v_lshlrev_b32_e32 v1, 5, v183
	v_lshlrev_b32_e32 v0, 8, v0
	v_and_b32_e32 v1, 0x80, v1
	v_add3_u32 v32, 0, v0, v1
	s_waitcnt lgkmcnt(0)
	s_barrier
	ds_read_b128 v[28:31], v32
	ds_read_b128 v[24:27], v32 offset:16
	ds_read_b128 v[20:23], v32 offset:32
	ds_read_b128 v[16:19], v32 offset:48
	ds_read_b128 v[12:15], v32 offset:64
	ds_read_b128 v[8:11], v32 offset:80
	s_waitcnt lgkmcnt(5)
	v_mul_f32_e32 v0, v29, v29
	s_waitcnt lgkmcnt(4)
	v_mul_f32_e32 v1, v25, v25
	v_fmac_f32_e32 v0, v28, v28
	v_fmac_f32_e32 v1, v24, v24
	v_fmac_f32_e32 v0, v30, v30
	v_fmac_f32_e32 v1, v26, v26
	v_fmac_f32_e32 v0, v31, v31
	v_fmac_f32_e32 v1, v27, v27
	v_add_f32_e32 v0, v0, v1
	s_waitcnt lgkmcnt(3)
	v_mul_f32_e32 v1, v21, v21
	v_fmac_f32_e32 v1, v20, v20
	v_fmac_f32_e32 v1, v22, v22
	v_fmac_f32_e32 v1, v23, v23
	v_add_f32_e32 v0, v0, v1
	s_waitcnt lgkmcnt(2)
	v_mul_f32_e32 v1, v17, v17
	v_fmac_f32_e32 v1, v16, v16
	v_fmac_f32_e32 v1, v18, v18
	v_fmac_f32_e32 v1, v19, v19
	s_waitcnt lgkmcnt(1)
	v_mov_b32_e32 v2, v13
	s_waitcnt lgkmcnt(0)
	v_mov_b32_e32 v3, v9
	v_add_f32_e32 v4, v0, v1
	v_mov_b32_e32 v0, v12
	v_mov_b32_e32 v1, v8
	v_pk_mul_f32 v[2:3], v[2:3], v[2:3]
	v_lshlrev_b32_e32 v36, 5, v202
	v_pk_fma_f32 v[0:1], v[0:1], v[0:1], v[2:3]
	v_mov_b32_e32 v2, v14
	v_mov_b32_e32 v3, v10
	v_pk_fma_f32 v[0:1], v[2:3], v[2:3], v[0:1]
	v_mov_b32_e32 v2, v15
	v_mov_b32_e32 v3, v11
	v_pk_fma_f32 v[0:1], v[2:3], v[2:3], v[0:1]
	v_lshlrev_b32_e32 v41, 2, v36
	v_add_f32_e32 v0, v4, v0
	v_add_f32_e32 v37, v0, v1
	ds_read_b128 v[4:7], v32 offset:96
	ds_read_b128 v[0:3], v32 offset:112
	s_waitcnt vmcnt(0)
	v_lshlrev_b32_e32 v42, 16, v76
	s_waitcnt lgkmcnt(1)
	v_mov_b32_e32 v34, v5
	s_waitcnt lgkmcnt(0)
	v_mov_b32_e32 v35, v1
	v_mov_b32_e32 v32, v4
	v_mov_b32_e32 v33, v0
	v_pk_mul_f32 v[34:35], v[34:35], v[34:35]
	s_nop 0
	v_pk_fma_f32 v[32:33], v[32:33], v[32:33], v[34:35]
	v_mov_b32_e32 v34, v6
	v_mov_b32_e32 v35, v2
	v_pk_fma_f32 v[32:33], v[34:35], v[34:35], v[32:33]
	v_mov_b32_e32 v34, v7
	v_mov_b32_e32 v35, v3
	v_pk_fma_f32 v[32:33], v[34:35], v[34:35], v[32:33]
	s_nop 0
	v_add_f32_e32 v32, v37, v32
	v_add_f32_e32 v32, v32, v33
	v_xor_b32_e32 v33, 1, v193
	v_cmp_lt_i32_e32 vcc, v33, v180
	s_nop 1
	v_cndmask_b32_e32 v33, v193, v33, vcc
	v_lshlrev_b32_e32 v33, 2, v33
	ds_bpermute_b32 v33, v33, v32
	s_waitcnt lgkmcnt(0)
	v_add_f32_e32 v32, v32, v33
	v_xor_b32_e32 v33, 2, v193
	v_cmp_lt_i32_e32 vcc, v33, v180
	s_nop 1
	v_cndmask_b32_e32 v33, v193, v33, vcc
	v_lshlrev_b32_e32 v33, 2, v33
	ds_bpermute_b32 v33, v33, v32
	s_waitcnt lgkmcnt(0)
	v_add_f32_e32 v32, v32, v33
	v_fmamk_f32 v32, v32, 0x3c000000, v191
	v_rsq_f32_e32 v32, v32
	s_nop 0
	v_mul_f32_e32 v40, v179, v32
	s_waitcnt vmcnt(0)
	v_mov_b32_e32 v32, v216
	v_mov_b32_e32 v33, v217
	v_mov_b32_e32 v34, v218
	v_mov_b32_e32 v35, v219
	v_mov_b32_e32 v36, v212
	v_mov_b32_e32 v37, v213
	v_mov_b32_e32 v38, v214
	v_mov_b32_e32 v39, v215
	v_mul_f32_e32 v43, v28, v40
	v_mul_f32_e32 v28, 0xbfb8aa3b, v42
	v_exp_f32_e32 v28, v28
	v_mul_f32_e32 v29, v29, v40
	v_mul_f32_e32 v31, v31, v40
	v_mul_f32_e32 v25, v25, v40
	v_add_f32_e32 v28, 1.0, v28
	v_rcp_f32_e32 v44, v28
	v_and_b32_e32 v28, 0xffff0000, v76
	v_mul_f32_e32 v21, v21, v40
	v_mul_f32_e32 v23, v23, v40
	v_mul_f32_e32 v17, v17, v40
	v_mul_f32_e32 v13, v13, v40
	v_mul_f32_e32 v15, v15, v40
	v_mul_f32_e32 v9, v9, v40
	v_mul_f32_e32 v5, v5, v40
	v_mul_f32_e32 v7, v7, v40
	v_mul_f32_e32 v1, v1, v40
	v_mov_b32_e32 v45, v36
	v_mul_f32_e32 v36, 0xbfb8aa3b, v28
	v_exp_f32_e32 v36, v36
	v_pk_mul_f32 v[42:43], v[44:45], v[42:43]
	v_add_f32_e32 v36, 1.0, v36
	v_rcp_f32_e32 v36, v36
	v_mul_f32_e32 v42, v42, v43
	v_mov_b32_e32 v43, v38
	v_pk_mul_f32 v[28:29], v[36:37], v[28:29]
	v_lshlrev_b32_e32 v36, 16, v77
	v_mul_f32_e32 v28, v28, v29
	v_mul_f32_e32 v29, 0xbfb8aa3b, v36
	v_exp_f32_e32 v29, v29
	v_cvt_pk_bf16_f32 v28, v42, v28
	v_mul_f32_e32 v37, v30, v40
	v_and_b32_e32 v30, 0xffff0000, v77
	v_add_f32_e32 v29, 1.0, v29
	v_rcp_f32_e32 v42, v29
	s_nop 0
	v_pk_mul_f32 v[36:37], v[42:43], v[36:37]
	s_nop 0
	v_mul_f32_e32 v29, v36, v37
	v_mul_f32_e32 v36, 0xbfb8aa3b, v30
	v_exp_f32_e32 v36, v36
	v_mov_b32_e32 v37, v32
	v_add_f32_e32 v36, 1.0, v36
	v_rcp_f32_e32 v38, v36
	s_nop 0
	v_pk_mul_f32 v[30:31], v[38:39], v[30:31]
	s_nop 0
	v_mul_f32_e32 v30, v30, v31
	v_cvt_pk_bf16_f32 v29, v29, v30
	v_lshlrev_b32_e32 v30, 16, v78
	v_mul_f32_e32 v31, v24, v40
	v_mul_f32_e32 v24, 0xbfb8aa3b, v30
	v_exp_f32_e32 v24, v24
	s_nop 0
	v_add_f32_e32 v24, 1.0, v24
	v_rcp_f32_e32 v36, v24
	v_and_b32_e32 v24, 0xffff0000, v78
	v_pk_mul_f32 v[30:31], v[36:37], v[30:31]
	s_nop 0
	v_mul_f32_e32 v30, v30, v31
	v_mul_f32_e32 v31, 0xbfb8aa3b, v24
	v_exp_f32_e32 v31, v31
	s_nop 0
	v_add_f32_e32 v31, 1.0, v31
	v_rcp_f32_e32 v32, v31
	s_nop 0
	v_pk_mul_f32 v[24:25], v[32:33], v[24:25]
	s_nop 0
	v_mul_f32_e32 v24, v24, v25
	v_cvt_pk_bf16_f32 v30, v30, v24
	v_lshlrev_b32_e32 v24, 16, v79
	v_mul_f32_e32 v25, v26, v40
; __device__ __forceinline__ float bflo(unsigned w) { return __uint_as_float(w << 16); }
; __device__ __forceinline__ float bfhi(unsigned w) { return __uint_as_float(w & 0xffff0000u); }
; __device__ __forceinline__ float silu(float z) { return z * __builtin_amdgcn_rcpf(1.f + __builtin_amdgcn_exp2f(-1.4426950408889634f * z)); }
; template <bool SH> __device__ __forceinline__ void attn_unit(bf16_t* __restrict__ proj, int tok0, int kv0, int seq, int h, float lam, float oscale, const float* __restrict__ subg, char* lds, bool dry) {
;     ...
;     for (int i = 0; i < 4; ++i) {
;       const u32x4 z = zg[i];
;       const f32x4 a0 = a[2 * i], a1 = a[2 * i + 1]; const f32x4 g0 = *(const f32x4*)(gg + i * 8), g1 = *(const f32x4*)(gg + i * 8 + 4);
;       u32x4 wv;
;       wv.x = cvtpk(a0[0] * rn * g0[0] * silu(bflo(z.x)), a0[1] * rn * g0[1] * silu(bfhi(z.x)));
;       wv.y = cvtpk(a0[2] * rn * g0[2] * silu(bflo(z.y)), a0[3] * rn * g0[3] * silu(bfhi(z.y)));
;       wv.z = cvtpk(a1[0] * rn * g1[0] * silu(bflo(z.z)), a1[1] * rn * g1[1] * silu(bfhi(z.z)));
;       wv.w = cvtpk(a1[2] * rn * g1[2] * silu(bflo(z.w)), a1[3] * rn * g1[3] * silu(bfhi(z.w)));
;       if (!dry) *(u32x4*)(zp + i * 8) = wv;
	v_mul_f32_e32 v26, 0xbfb8aa3b, v24
	v_exp_f32_e32 v26, v26
	v_mov_b32_e32 v33, v34
	v_add_f32_e32 v26, 1.0, v26
	v_rcp_f32_e32 v32, v26
	s_nop 0
	v_pk_mul_f32 v[24:25], v[32:33], v[24:25]
	s_nop 0
	v_mul_f32_e32 v26, v24, v25
	v_and_b32_e32 v24, 0xffff0000, v79
	v_mul_f32_e32 v25, v27, v40
	v_mul_f32_e32 v27, 0xbfb8aa3b, v24
	v_exp_f32_e32 v27, v27
	v_lshlrev_b32_e32 v32, 16, v72
	v_mul_f32_e32 v33, v20, v40
	v_mul_f32_e32 v20, 0xbfb8aa3b, v32
	v_add_f32_e32 v27, 1.0, v27
	v_rcp_f32_e32 v34, v27
	v_exp_f32_e32 v20, v20
	v_pk_mul_f32 v[24:25], v[34:35], v[24:25]
	s_nop 0
	v_mul_f32_e32 v24, v24, v25
	v_cvt_pk_bf16_f32 v31, v26, v24
	global_store_dwordx4 v[80:81], v[28:31], off offset:1024
	v_mov_b32_e32 v24, v224
	v_mov_b32_e32 v25, v225
	v_mov_b32_e32 v26, v226
	v_mov_b32_e32 v27, v227
	s_nop 0
	v_mov_b32_e32 v28, v220
	v_mov_b32_e32 v29, v221
	v_mov_b32_e32 v30, v222
	v_mov_b32_e32 v31, v223
	v_add_f32_e32 v20, 1.0, v20
	v_rcp_f32_e32 v34, v20
	v_and_b32_e32 v20, 0xffff0000, v72
	v_mov_b32_e32 v35, v28
	v_mul_f32_e32 v28, 0xbfb8aa3b, v20
	v_exp_f32_e32 v28, v28
	v_pk_mul_f32 v[32:33], v[34:35], v[32:33]
	v_add_f32_e32 v28, 1.0, v28
	v_rcp_f32_e32 v28, v28
	v_mul_f32_e32 v32, v32, v33
	v_mov_b32_e32 v33, v30
	v_pk_mul_f32 v[20:21], v[28:29], v[20:21]
	v_lshlrev_b32_e32 v28, 16, v73
	v_mul_f32_e32 v20, v20, v21
	v_mul_f32_e32 v21, 0xbfb8aa3b, v28
	v_exp_f32_e32 v21, v21
	v_cvt_pk_bf16_f32 v20, v32, v20
	v_mul_f32_e32 v29, v22, v40
	v_and_b32_e32 v22, 0xffff0000, v73
	v_add_f32_e32 v21, 1.0, v21
	v_rcp_f32_e32 v32, v21
	s_nop 0
	v_pk_mul_f32 v[28:29], v[32:33], v[28:29]
	s_nop 0
	v_mul_f32_e32 v21, v28, v29
	v_mul_f32_e32 v28, 0xbfb8aa3b, v22
	v_exp_f32_e32 v28, v28
	v_mov_b32_e32 v29, v24
	v_add_f32_e32 v28, 1.0, v28
	v_rcp_f32_e32 v30, v28
	s_nop 0
	v_pk_mul_f32 v[22:23], v[30:31], v[22:23]
	s_nop 0
	v_mul_f32_e32 v22, v22, v23
	v_cvt_pk_bf16_f32 v21, v21, v22
	v_lshlrev_b32_e32 v22, 16, v74
	v_mul_f32_e32 v23, v16, v40
	v_mul_f32_e32 v16, 0xbfb8aa3b, v22
	v_exp_f32_e32 v16, v16
	s_nop 0
	v_add_f32_e32 v16, 1.0, v16
	v_rcp_f32_e32 v28, v16
	v_and_b32_e32 v16, 0xffff0000, v74
	v_pk_mul_f32 v[22:23], v[28:29], v[22:23]
	s_nop 0
	v_mul_f32_e32 v22, v22, v23
	v_mul_f32_e32 v23, 0xbfb8aa3b, v16
	v_exp_f32_e32 v23, v23
	s_nop 0
	v_add_f32_e32 v23, 1.0, v23
	v_rcp_f32_e32 v24, v23
	s_nop 0
	v_pk_mul_f32 v[16:17], v[24:25], v[16:17]
	s_nop 0
	v_mul_f32_e32 v16, v16, v17
	v_cvt_pk_bf16_f32 v22, v22, v16
	v_lshlrev_b32_e32 v16, 16, v75
	v_mul_f32_e32 v17, v18, v40
	v_mul_f32_e32 v18, 0xbfb8aa3b, v16
	v_exp_f32_e32 v18, v18
	v_mov_b32_e32 v25, v26
	v_add_f32_e32 v18, 1.0, v18
	v_rcp_f32_e32 v24, v18
	s_nop 0
	v_pk_mul_f32 v[16:17], v[24:25], v[16:17]
	s_nop 0
	v_mul_f32_e32 v18, v16, v17
	v_and_b32_e32 v16, 0xffff0000, v75
	v_mul_f32_e32 v17, v19, v40
	v_mul_f32_e32 v19, 0xbfb8aa3b, v16
	v_exp_f32_e32 v19, v19
	v_mul_f32_e32 v25, v12, v40
	v_add_f32_e32 v19, 1.0, v19
	v_rcp_f32_e32 v26, v19
	s_nop 0
	v_pk_mul_f32 v[16:17], v[26:27], v[16:17]
	s_nop 0
	v_mul_f32_e32 v16, v16, v17
	v_cvt_pk_bf16_f32 v23, v18, v16
	global_store_dwordx4 v[80:81], v[20:23], off offset:1040
	v_mov_b32_e32 v16, v232
	v_mov_b32_e32 v17, v233
	v_mov_b32_e32 v18, v234
	v_mov_b32_e32 v19, v235
	s_nop 0
	v_mov_b32_e32 v20, v228
	v_mov_b32_e32 v21, v229
	v_mov_b32_e32 v22, v230
	v_mov_b32_e32 v23, v231
	v_lshlrev_b32_e32 v26, 16, v68
	v_mul_f32_e32 v12, 0xbfb8aa3b, v26
	v_exp_f32_e32 v12, v12
	v_mov_b32_e32 v27, v20
	v_add_f32_e32 v12, 1.0, v12
	v_and_b32_e32 v20, 0xffff0000, v68
	v_rcp_f32_e32 v24, v12
	v_mul_f32_e32 v12, 0xbfb8aa3b, v20
	v_exp_f32_e32 v12, v12
	v_pk_mul_f32 v[24:25], v[24:25], v[26:27]
	s_nop 0
	v_mul_f32_e32 v24, v24, v25
	v_add_f32_e32 v12, 1.0, v12
	v_rcp_f32_e32 v12, v12
	v_mov_b32_e32 v25, v22
	v_and_b32_e32 v22, 0xffff0000, v69
	v_pk_mul_f32 v[12:13], v[12:13], v[20:21]
	s_nop 0
	v_mul_f32_e32 v12, v12, v13
	v_cvt_pk_bf16_f32 v12, v24, v12
	v_lshlrev_b32_e32 v24, 16, v69
; __device__ __forceinline__ float bflo(unsigned w) { return __uint_as_float(w << 16); }
; __device__ __forceinline__ float bfhi(unsigned w) { return __uint_as_float(w & 0xffff0000u); }
; __device__ __forceinline__ float silu(float z) { return z * __builtin_amdgcn_rcpf(1.f + __builtin_amdgcn_exp2f(-1.4426950408889634f * z)); }
; template <bool SH> __device__ __forceinline__ void attn_unit(bf16_t* __restrict__ proj, int tok0, int kv0, int seq, int h, float lam, float oscale, const float* __restrict__ subg, char* lds, bool dry) {
;     ...
;     for (int i = 0; i < 4; ++i) {
;       const u32x4 z = zg[i];
;       const f32x4 a0 = a[2 * i], a1 = a[2 * i + 1]; const f32x4 g0 = *(const f32x4*)(gg + i * 8), g1 = *(const f32x4*)(gg + i * 8 + 4);
;       u32x4 wv;
;       wv.x = cvtpk(a0[0] * rn * g0[0] * silu(bflo(z.x)), a0[1] * rn * g0[1] * silu(bfhi(z.x)));
;       wv.y = cvtpk(a0[2] * rn * g0[2] * silu(bflo(z.y)), a0[3] * rn * g0[3] * silu(bfhi(z.y)));
;       wv.z = cvtpk(a1[0] * rn * g1[0] * silu(bflo(z.z)), a1[1] * rn * g1[1] * silu(bfhi(z.z)));
;       wv.w = cvtpk(a1[2] * rn * g1[2] * silu(bflo(z.w)), a1[3] * rn * g1[3] * silu(bfhi(z.w)));
;       if (!dry) *(u32x4*)(zp + i * 8) = wv;
;     }
;   }
;   __syncthreads();
	v_mul_f32_e32 v13, 0xbfb8aa3b, v24
	v_mul_f32_e32 v21, v14, v40
	v_exp_f32_e32 v13, v13
	v_mul_f32_e32 v14, 0xbfb8aa3b, v22
	v_exp_f32_e32 v14, v14
	v_add_f32_e32 v13, 1.0, v13
	v_rcp_f32_e32 v20, v13
	v_add_f32_e32 v14, 1.0, v14
	v_rcp_f32_e32 v14, v14
	v_pk_mul_f32 v[20:21], v[20:21], v[24:25]
	s_nop 0
	v_mul_f32_e32 v13, v20, v21
	v_pk_mul_f32 v[14:15], v[14:15], v[22:23]
	v_lshlrev_b32_e32 v20, 16, v70
	v_mul_f32_e32 v14, v14, v15
	v_mul_f32_e32 v15, v8, v40
	v_mul_f32_e32 v8, 0xbfb8aa3b, v20
	v_exp_f32_e32 v8, v8
	v_mov_b32_e32 v21, v16
	v_and_b32_e32 v16, 0xffff0000, v70
	v_cvt_pk_bf16_f32 v13, v13, v14
	v_add_f32_e32 v8, 1.0, v8
	v_rcp_f32_e32 v14, v8
	v_mul_f32_e32 v8, 0xbfb8aa3b, v16
	v_exp_f32_e32 v8, v8
	v_pk_mul_f32 v[14:15], v[14:15], v[20:21]
	s_nop 0
	v_mul_f32_e32 v14, v14, v15
	v_add_f32_e32 v8, 1.0, v8
	v_rcp_f32_e32 v8, v8
	s_nop 0
	v_pk_mul_f32 v[8:9], v[8:9], v[16:17]
	s_nop 0
	v_mul_f32_e32 v8, v8, v9
	v_lshlrev_b32_e32 v16, 16, v71
	v_cvt_pk_bf16_f32 v14, v14, v8
	v_mul_f32_e32 v8, 0xbfb8aa3b, v16
	v_exp_f32_e32 v8, v8
	v_mul_f32_e32 v9, v10, v40
	v_mov_b32_e32 v17, v18
	v_and_b32_e32 v18, 0xffff0000, v71
	v_add_f32_e32 v8, 1.0, v8
	v_rcp_f32_e32 v8, v8
	s_nop 0
	v_pk_mul_f32 v[8:9], v[8:9], v[16:17]
	s_nop 0
	v_mul_f32_e32 v10, v8, v9
	v_mul_f32_e32 v8, 0xbfb8aa3b, v18
	v_exp_f32_e32 v8, v8
	v_mul_f32_e32 v9, v11, v40
	v_mul_f32_e32 v17, v4, v40
	v_add_f32_e32 v8, 1.0, v8
	v_rcp_f32_e32 v8, v8
	s_nop 0
	v_pk_mul_f32 v[8:9], v[8:9], v[18:19]
	s_nop 0
	v_mul_f32_e32 v8, v8, v9
	v_cvt_pk_bf16_f32 v15, v10, v8
	global_store_dwordx4 v[80:81], v[12:15], off offset:1056
	v_mov_b32_e32 v8, v240
	v_mov_b32_e32 v9, v241
	v_mov_b32_e32 v10, v242
	v_mov_b32_e32 v11, v243
	s_nop 0
	v_mov_b32_e32 v12, v236
	v_mov_b32_e32 v13, v237
	v_mov_b32_e32 v14, v238
	v_mov_b32_e32 v15, v239
	v_lshlrev_b32_e32 v18, 16, v64
	v_mul_f32_e32 v4, 0xbfb8aa3b, v18
	v_exp_f32_e32 v4, v4
	v_mov_b32_e32 v19, v12
	v_add_f32_e32 v4, 1.0, v4
	v_and_b32_e32 v12, 0xffff0000, v64
	v_rcp_f32_e32 v16, v4
	v_mul_f32_e32 v4, 0xbfb8aa3b, v12
	v_exp_f32_e32 v4, v4
	v_pk_mul_f32 v[16:17], v[16:17], v[18:19]
	s_nop 0
	v_mul_f32_e32 v16, v16, v17
	v_add_f32_e32 v4, 1.0, v4
	v_rcp_f32_e32 v4, v4
	v_mov_b32_e32 v17, v14
	v_and_b32_e32 v14, 0xffff0000, v65
	v_pk_mul_f32 v[4:5], v[4:5], v[12:13]
	s_nop 0
	v_mul_f32_e32 v4, v4, v5
	v_cvt_pk_bf16_f32 v4, v16, v4
	v_lshlrev_b32_e32 v16, 16, v65
	v_mul_f32_e32 v5, 0xbfb8aa3b, v16
	v_mul_f32_e32 v13, v6, v40
	v_exp_f32_e32 v5, v5
	v_mul_f32_e32 v6, 0xbfb8aa3b, v14
	v_exp_f32_e32 v6, v6
	v_add_f32_e32 v5, 1.0, v5
	v_rcp_f32_e32 v12, v5
	v_add_f32_e32 v6, 1.0, v6
	v_rcp_f32_e32 v6, v6
	v_pk_mul_f32 v[12:13], v[12:13], v[16:17]
	s_nop 0
	v_mul_f32_e32 v5, v12, v13
	v_pk_mul_f32 v[6:7], v[6:7], v[14:15]
	v_lshlrev_b32_e32 v12, 16, v66
	v_mul_f32_e32 v6, v6, v7
	v_mul_f32_e32 v7, v0, v40
	v_mul_f32_e32 v0, 0xbfb8aa3b, v12
	v_exp_f32_e32 v0, v0
	v_mov_b32_e32 v13, v8
	v_and_b32_e32 v8, 0xffff0000, v66
	v_cvt_pk_bf16_f32 v5, v5, v6
	v_add_f32_e32 v0, 1.0, v0
	v_rcp_f32_e32 v6, v0
	v_mul_f32_e32 v0, 0xbfb8aa3b, v8
	v_exp_f32_e32 v0, v0
	v_pk_mul_f32 v[6:7], v[6:7], v[12:13]
	s_nop 0
	v_mul_f32_e32 v6, v6, v7
	v_add_f32_e32 v0, 1.0, v0
	v_rcp_f32_e32 v0, v0
	s_nop 0
	v_pk_mul_f32 v[0:1], v[0:1], v[8:9]
	s_nop 0
	v_mul_f32_e32 v0, v0, v1
	v_lshlrev_b32_e32 v8, 16, v67
	v_cvt_pk_bf16_f32 v6, v6, v0
	v_mul_f32_e32 v0, 0xbfb8aa3b, v8
	v_exp_f32_e32 v0, v0
	v_mul_f32_e32 v1, v2, v40
	v_mov_b32_e32 v9, v10
	v_and_b32_e32 v10, 0xffff0000, v67
	v_add_f32_e32 v0, 1.0, v0
	v_rcp_f32_e32 v0, v0
	s_nop 0
	v_pk_mul_f32 v[0:1], v[0:1], v[8:9]
	s_nop 0
	v_mul_f32_e32 v2, v0, v1
	v_mul_f32_e32 v0, 0xbfb8aa3b, v10
	v_exp_f32_e32 v0, v0
	v_mul_f32_e32 v1, v3, v40
	v_add_f32_e32 v0, 1.0, v0
	v_rcp_f32_e32 v0, v0
	s_nop 0
	v_pk_mul_f32 v[0:1], v[0:1], v[10:11]
	s_nop 0
	v_mul_f32_e32 v0, v0, v1
	v_cvt_pk_bf16_f32 v7, v2, v0
	global_store_dwordx4 v[80:81], v[4:7], off offset:1072
	s_barrier

; __device__ void attn_phase(const Params& p, int l, char* lds, bool dry = false) {
;     ...
;     if (need) attn_unit<true>(p.proj, tok0, kv0, seq, h, lam, oscale, subg, lds, dry);
;     else attn_unit<false>(p.proj, tok0, kv0, seq, h, lam, oscale, subg, lds, dry);
.LBB0_315:
	s_cbranch_execz .LBB0_298
	s_branch .LBB0_353
	s_nop 0
	s_nop 0
	s_nop 0
	s_nop 0

; __device__ __forceinline__ void qkt_k(f32x16& p0, f32x16& p1, const char* Ks, const bf16x8* kf, const bf16x8* qr, int r32, int hi, int mapB) {
;   p0 = f32x16{}; p1 = f32x16{};
;   p0 = __builtin_amdgcn_mfma_f32_32x32x16_bf16(kf[0], qr[0], p0, 0, 0, 0);
;   p1 = __builtin_amdgcn_mfma_f32_32x32x16_bf16(kf[1], qr[0], p1, 0, 0, 0);
; #pragma unroll
;   for (int d0 = 1; d0 < 4; ++d0) { const int cb = (d0 * 16 + hi * 8) * 2 + mapB;
;     bf16x8 b0 = *reinterpret_cast<const bf16x8*>(Ks + KSWZ(r32, cb));
;     bf16x8 b1 = *reinterpret_cast<const bf16x8*>(Ks + KSWZ(32 + r32, cb));
;     p0 = __builtin_amdgcn_mfma_f32_32x32x16_bf16(b0, qr[d0], p0, 0, 0, 0);
;     p1 = __builtin_amdgcn_mfma_f32_32x32x16_bf16(b1, qr[d0], p1, 0, 0, 0); }
; }
.LBB0_355:
	s_add_i32 s21, s20, 0xffff8000
	s_waitcnt lgkmcnt(0)
	s_and_b32 s21, s21, 0x10000
	s_xor_b32 s26, s21, 0x10000
	v_add_u32_e32 v160, s26, v208
	ds_read_b64_tr_b16 v[112:113], v160 offset:0x200
	ds_read_b64_tr_b16 v[114:115], v160 offset:0xa00
	ds_read_b64_tr_b16 v[116:117], v160 offset:0x1200
	ds_read_b64_tr_b16 v[118:119], v160 offset:0x1a00
	ds_read_b64_tr_b16 v[120:121], v160 offset:0x2200
	ds_read_b64_tr_b16 v[122:123], v160 offset:0x2a00
	ds_read_b64_tr_b16 v[124:125], v160 offset:0x3200
	ds_read_b64_tr_b16 v[126:127], v160 offset:0x3a00
	v_mfma_f32_32x32x16_bf16 v[48:63], v[108:111], v[156:159], v[48:63]
	s_and_b32 s27, s20, 0x18000
	s_add_i32 s27, s27, 0
	s_add_i32 s26, s27, s17
	s_setprio 3
	s_mov_b32 s58, m0
	s_mov_b32 m0, s26
	s_nop 0
	global_load_lds_dwordx4 v166, s[12:13]
	s_mov_b32 m0, s58
	s_setprio 0
	s_add_u32 s58, s12, 0xfffe8000
	s_addc_u32 s59, s13, -1
	s_add_i32 s60, s27, s19
	v_mfma_f32_32x32x16_bf16 v[48:63], v[104:107], v[152:155], v[48:63]
	s_setprio 3
	s_mov_b32 s61, m0
	s_mov_b32 m0, s60
	s_nop 0
	global_load_lds_dwordx4 v166, s[58:59]
	s_mov_b32 m0, s61
	s_setprio 0
	v_mfma_f32_32x32x16_bf16 v[48:63], v[100:103], v[148:151], v[48:63]
	v_mfma_f32_32x32x16_bf16 v[48:63], v[96:99], v[144:147], v[48:63]
	s_waitcnt lgkmcnt(0)
	ds_read_b64_tr_b16 v[144:145], v160 offset:0x400
	ds_read_b64_tr_b16 v[146:147], v160 offset:0xc00
	ds_read_b64_tr_b16 v[148:149], v160 offset:0x1400
	ds_read_b64_tr_b16 v[150:151], v160 offset:0x1c00
	ds_read_b64_tr_b16 v[152:153], v160 offset:0x2400
	ds_read_b64_tr_b16 v[154:155], v160 offset:0x2c00
	ds_read_b64_tr_b16 v[156:157], v160 offset:0x3400
	ds_read_b64_tr_b16 v[158:159], v160 offset:0x3c00
	v_mfma_f32_32x32x16_bf16 v[32:47], v[108:111], v[112:115], v[32:47]
	s_add_u32 s58, s12, 0x30000
	s_addc_u32 s59, s13, 0
	s_add_i32 s61, s26, 0x2000
	s_setprio 3
	s_mov_b32 s64, m0
	s_mov_b32 m0, s61
	s_nop 0
	global_load_lds_dwordx4 v166, s[58:59]
	s_mov_b32 m0, s64
	s_setprio 0
	s_add_u32 s58, s12, 0x18000
	s_addc_u32 s59, s13, 0
	s_addk_i32 s60, 0x2000
	v_mfma_f32_32x32x16_bf16 v[32:47], v[104:107], v[116:119], v[32:47]
	s_setprio 3
	s_mov_b32 s61, m0
	s_mov_b32 m0, s60
	s_nop 0
	global_load_lds_dwordx4 v166, s[58:59]
	s_mov_b32 m0, s61
	s_setprio 0
	v_mfma_f32_32x32x16_bf16 v[32:47], v[100:103], v[120:123], v[32:47]
	v_mfma_f32_32x32x16_bf16 v[32:47], v[96:99], v[124:127], v[32:47]
	s_waitcnt lgkmcnt(0)
	ds_read_b64_tr_b16 v[112:113], v160 offset:0x600
	ds_read_b64_tr_b16 v[114:115], v160 offset:0xe00
	ds_read_b64_tr_b16 v[116:117], v160 offset:0x1600
	ds_read_b64_tr_b16 v[118:119], v160 offset:0x1e00
	ds_read_b64_tr_b16 v[120:121], v160 offset:0x2600
	ds_read_b64_tr_b16 v[122:123], v160 offset:0x2e00
	ds_read_b64_tr_b16 v[124:125], v160 offset:0x3600
	ds_read_b64_tr_b16 v[126:127], v160 offset:0x3e00
	v_mfma_f32_32x32x16_bf16 v[16:31], v[108:111], v[144:147], v[16:31]
	s_add_u32 s58, s12, 0x400
	s_addc_u32 s59, s13, 0
	s_add_i32 s60, s26, 0x4000
	s_setprio 3
	s_mov_b32 s61, m0
	s_mov_b32 m0, s60
	s_nop 0
	global_load_lds_dwordx4 v207, s[58:59]
	s_mov_b32 m0, s61
	s_setprio 0
	v_mfma_f32_32x32x16_bf16 v[16:31], v[104:107], v[148:151], v[16:31]
	v_mfma_f32_32x32x16_bf16 v[16:31], v[100:103], v[152:155], v[16:31]
	v_mfma_f32_32x32x16_bf16 v[16:31], v[96:99], v[156:159], v[16:31]
	s_waitcnt lgkmcnt(0)
	v_mfma_f32_32x32x16_bf16 v[0:15], v[108:111], v[112:115], v[0:15]
	s_add_u32 s58, s12, 0x30400
	s_addc_u32 s59, s13, 0
	s_addk_i32 s26, 0x6000
	s_setprio 3
	s_mov_b32 s60, m0
	s_mov_b32 m0, s26
	s_nop 0
	global_load_lds_dwordx4 v207, s[58:59]
	s_mov_b32 m0, s60
	s_setprio 0
	s_add_i32 s26, s21, 0
	v_add_u32_e32 v160, s26, v165
	v_mfma_f32_32x32x16_bf16 v[0:15], v[104:107], v[116:119], v[0:15]
	v_mfma_f32_32x32x16_bf16 v[0:15], v[100:103], v[120:123], v[0:15]
	ds_read_b128 v[100:103], v160
	ds_read_b128 v[112:115], v160 offset:8192
	v_mfma_f32_32x32x16_bf16 v[0:15], v[96:99], v[124:127], v[0:15]
	s_setprio 1
	v_add_u32_e32 v148, s26, v164
	ds_read_b128 v[144:147], v148
	ds_read_b128 v[148:151], v148 offset:8192
	v_exp_f32_e32 v64, v64
	v_exp_f32_e32 v65, v65
	v_exp_f32_e32 v66, v66
	v_exp_f32_e32 v67, v67
	s_waitcnt lgkmcnt(3)
	v_mfma_f32_32x32x16_bf16 v[96:111], v[100:103], v[140:143], 0
	v_exp_f32_e32 v68, v68
	v_add_f32_e32 v172, 0, v64
	v_exp_f32_e32 v69, v69
	v_add_f32_e32 v172, v65, v172
	v_exp_f32_e32 v70, v70
	v_add_f32_e32 v172, v66, v172
	v_exp_f32_e32 v71, v71
	v_add_f32_e32 v172, v67, v172
	v_exp_f32_e32 v72, v72
	s_waitcnt lgkmcnt(2)
	v_mfma_f32_32x32x16_bf16 v[112:127], v[112:115], v[140:143], 0
	v_add_u32_e32 v156, s26, v163
	ds_read_b128 v[152:155], v156
	ds_read_b128 v[156:159], v156 offset:8192
	v_add_f32_e32 v172, v68, v172
	v_exp_f32_e32 v73, v73
	v_add_f32_e32 v172, v69, v172
	v_exp_f32_e32 v74, v74
	v_add_f32_e32 v172, v70, v172
	v_exp_f32_e32 v75, v75
	v_add_f32_e32 v172, v71, v172
	v_exp_f32_e32 v76, v76
	v_add_f32_e32 v172, v72, v172
	s_waitcnt lgkmcnt(3)
	v_mfma_f32_32x32x16_bf16 v[96:111], v[144:147], v[136:139], v[96:111]
	v_exp_f32_e32 v77, v77
	v_add_f32_e32 v172, v73, v172
	v_exp_f32_e32 v78, v78
	v_add_f32_e32 v172, v74, v172
	v_exp_f32_e32 v79, v79
	v_add_f32_e32 v172, v75, v172
	v_exp_f32_e32 v80, v80
	v_add_f32_e32 v172, v76, v172
	v_exp_f32_e32 v81, v81
	s_waitcnt lgkmcnt(2)
	v_mfma_f32_32x32x16_bf16 v[112:127], v[148:151], v[136:139], v[112:127]
	v_add_u32_e32 v148, s26, v162
	ds_read_b128 v[144:147], v148
	ds_read_b128 v[148:151], v148 offset:8192
	v_add_f32_e32 v172, v77, v172
	v_exp_f32_e32 v82, v82
	v_add_f32_e32 v172, v78, v172
	v_exp_f32_e32 v83, v83
	v_add_f32_e32 v172, v79, v172
	v_exp_f32_e32 v84, v84
	v_add_f32_e32 v172, v80, v172
	v_exp_f32_e32 v85, v85
	v_add_f32_e32 v172, v81, v172
	v_exp_f32_e32 v86, v86
	s_waitcnt lgkmcnt(3)
; __device__ __forceinline__ void qkt_k(f32x16& p0, f32x16& p1, const char* Ks, const bf16x8* kf, const bf16x8* qr, int r32, int hi, int mapB) {
;   p0 = f32x16{}; p1 = f32x16{};
;   p0 = __builtin_amdgcn_mfma_f32_32x32x16_bf16(kf[0], qr[0], p0, 0, 0, 0);
;   p1 = __builtin_amdgcn_mfma_f32_32x32x16_bf16(kf[1], qr[0], p1, 0, 0, 0);
; #pragma unroll
;   for (int d0 = 1; d0 < 4; ++d0) { const int cb = (d0 * 16 + hi * 8) * 2 + mapB;
;     bf16x8 b0 = *reinterpret_cast<const bf16x8*>(Ks + KSWZ(r32, cb));
;     bf16x8 b1 = *reinterpret_cast<const bf16x8*>(Ks + KSWZ(32 + r32, cb));
;     p0 = __builtin_amdgcn_mfma_f32_32x32x16_bf16(b0, qr[d0], p0, 0, 0, 0);
;     p1 = __builtin_amdgcn_mfma_f32_32x32x16_bf16(b1, qr[d0], p1, 0, 0, 0); }
; }
	v_mfma_f32_32x32x16_bf16 v[96:111], v[152:155], v[132:135], v[96:111]
	v_add_f32_e32 v172, v82, v172
	v_exp_f32_e32 v87, v87
	v_add_f32_e32 v172, v83, v172
	v_exp_f32_e32 v88, v88
	v_add_f32_e32 v172, v84, v172
	v_exp_f32_e32 v89, v89
	v_add_f32_e32 v172, v85, v172
	v_exp_f32_e32 v90, v90
	v_add_f32_e32 v172, v86, v172
	s_waitcnt lgkmcnt(2)
	v_mfma_f32_32x32x16_bf16 v[112:127], v[156:159], v[132:135], v[112:127]
	s_add_i32 s26, s20, 0x10000
	s_and_b32 s58, s26, 0x18000
	v_add_u32_e32 v161, s58, v208
	ds_read_b64_tr_b16 v[152:153], v161 offset:0x2000
	ds_read_b64_tr_b16 v[154:155], v161 offset:0x2800
	ds_read_b64_tr_b16 v[156:157], v161 offset:0x3000
	ds_read_b64_tr_b16 v[158:159], v161 offset:0x3800
	v_exp_f32_e32 v91, v91
	v_add_f32_e32 v172, v87, v172
	v_exp_f32_e32 v92, v92
	v_add_f32_e32 v172, v88, v172
	v_exp_f32_e32 v93, v93
	v_add_f32_e32 v172, v89, v172
	v_exp_f32_e32 v94, v94
	v_add_f32_e32 v172, v90, v172
	v_exp_f32_e32 v95, v95
	s_waitcnt lgkmcnt(5)
	v_mfma_f32_32x32x16_bf16 v[96:111], v[144:147], v[128:131], v[96:111]
	ds_read_b64_tr_b16 v[144:145], v161 offset:0
	ds_read_b64_tr_b16 v[146:147], v161 offset:0x800
	v_add_f32_e32 v172, v91, v172
	v_add_f32_e32 v172, v92, v172
	v_add_f32_e32 v172, v93, v172
	v_add_f32_e32 v172, v94, v172
	v_add_f32_e32 v172, v95, v172
	v_add_f32_e32 v171, v171, v172
	v_cvt_pk_bf16_f32 v64, v64, v65
	v_cvt_pk_bf16_f32 v65, v66, v67
	v_cvt_pk_bf16_f32 v66, v68, v69
	v_cvt_pk_bf16_f32 v67, v70, v71
	v_cvt_pk_bf16_f32 v68, v72, v73
	v_cvt_pk_bf16_f32 v69, v74, v75
	s_waitcnt lgkmcnt(6)
	v_mfma_f32_32x32x16_bf16 v[112:127], v[148:151], v[128:131], v[112:127]
	ds_read_b64_tr_b16 v[148:149], v161 offset:0x1000
	ds_read_b64_tr_b16 v[150:151], v161 offset:0x1800
	v_cvt_pk_bf16_f32 v70, v76, v77
	v_cvt_pk_bf16_f32 v71, v78, v79
	v_cvt_pk_bf16_f32 v72, v80, v81
	v_cvt_pk_bf16_f32 v73, v82, v83
	v_cvt_pk_bf16_f32 v74, v84, v85
	v_cvt_pk_bf16_f32 v75, v86, v87
	v_cvt_pk_bf16_f32 v76, v88, v89
	v_cvt_pk_bf16_f32 v77, v90, v91
	v_cvt_pk_bf16_f32 v78, v92, v93
	v_cvt_pk_bf16_f32 v79, v94, v95
	s_setprio 0
	s_waitcnt vmcnt(0)
	s_barrier
	s_waitcnt lgkmcnt(0)
	ds_read_b64_tr_b16 v[80:81], v161 offset:0x200
	ds_read_b64_tr_b16 v[82:83], v161 offset:0xa00
	ds_read_b64_tr_b16 v[84:85], v161 offset:0x1200
	ds_read_b64_tr_b16 v[86:87], v161 offset:0x1a00
	ds_read_b64_tr_b16 v[88:89], v161 offset:0x2200
	ds_read_b64_tr_b16 v[90:91], v161 offset:0x2a00
	ds_read_b64_tr_b16 v[92:93], v161 offset:0x3200
	ds_read_b64_tr_b16 v[94:95], v161 offset:0x3a00
	v_mfma_f32_32x32x16_bf16 v[48:63], v[64:67], v[144:147], v[48:63]
	s_add_u32 s58, s12, 0x60000
	s_addc_u32 s59, s13, 0
	s_add_i32 s20, s20, 0x8000
	s_and_b32 s20, s20, 0x10000
	s_add_i32 s20, s20, 0
	s_add_i32 s60, s20, s17
	s_setprio 3
	s_mov_b32 s61, m0
	s_mov_b32 m0, s60
	s_nop 0
	global_load_lds_dwordx4 v166, s[58:59]
	s_mov_b32 m0, s61
	s_setprio 0
	v_mfma_f32_32x32x16_bf16 v[48:63], v[68:71], v[148:151], v[48:63]
	s_add_u32 s58, s12, 0x48000
	s_addc_u32 s59, s13, 0
	s_add_i32 s20, s20, s19
	s_setprio 3
	s_mov_b32 s61, m0
	s_mov_b32 m0, s20
	s_nop 0
	global_load_lds_dwordx4 v166, s[58:59]
	s_mov_b32 m0, s61
	s_setprio 0
	v_mfma_f32_32x32x16_bf16 v[48:63], v[72:75], v[152:155], v[48:63]
	v_mfma_f32_32x32x16_bf16 v[48:63], v[76:79], v[156:159], v[48:63]
	s_waitcnt lgkmcnt(0)
	ds_read_b64_tr_b16 v[144:145], v161 offset:0x400
	ds_read_b64_tr_b16 v[146:147], v161 offset:0xc00
	ds_read_b64_tr_b16 v[148:149], v161 offset:0x1400
	ds_read_b64_tr_b16 v[150:151], v161 offset:0x1c00
	ds_read_b64_tr_b16 v[152:153], v161 offset:0x2400
	ds_read_b64_tr_b16 v[154:155], v161 offset:0x2c00
	ds_read_b64_tr_b16 v[156:157], v161 offset:0x3400
	ds_read_b64_tr_b16 v[158:159], v161 offset:0x3c00
	v_mfma_f32_32x32x16_bf16 v[32:47], v[64:67], v[80:83], v[32:47]
	s_add_u32 s58, s12, 0x90000
	s_addc_u32 s59, s13, 0
	s_add_i32 s61, s60, 0x2000
	s_setprio 3
	s_mov_b32 s64, m0
	s_mov_b32 m0, s61
	s_nop 0
	global_load_lds_dwordx4 v166, s[58:59]
	s_mov_b32 m0, s64
	s_setprio 0
	s_add_u32 s58, s12, 0x78000
	s_addc_u32 s59, s13, 0
	s_addk_i32 s20, 0x2000
	v_mfma_f32_32x32x16_bf16 v[32:47], v[68:71], v[84:87], v[32:47]
	s_setprio 3
	s_mov_b32 s61, m0
	s_mov_b32 m0, s20
	s_nop 0
	global_load_lds_dwordx4 v166, s[58:59]
	s_mov_b32 m0, s61
	s_setprio 0
	v_mfma_f32_32x32x16_bf16 v[32:47], v[72:75], v[88:91], v[32:47]
	v_mfma_f32_32x32x16_bf16 v[32:47], v[76:79], v[92:95], v[32:47]
	s_waitcnt lgkmcnt(0)
	ds_read_b64_tr_b16 v[80:81], v161 offset:0x600
	ds_read_b64_tr_b16 v[82:83], v161 offset:0xe00
	ds_read_b64_tr_b16 v[84:85], v161 offset:0x1600
	ds_read_b64_tr_b16 v[86:87], v161 offset:0x1e00
	ds_read_b64_tr_b16 v[88:89], v161 offset:0x2600
	ds_read_b64_tr_b16 v[90:91], v161 offset:0x2e00
	ds_read_b64_tr_b16 v[92:93], v161 offset:0x3600
	ds_read_b64_tr_b16 v[94:95], v161 offset:0x3e00
	v_mfma_f32_32x32x16_bf16 v[16:31], v[64:67], v[144:147], v[16:31]
	s_add_u32 s58, s12, 0x60400
	s_addc_u32 s59, s13, 0
	s_add_i32 s20, s60, 0x4000
	s_setprio 3
	s_mov_b32 s61, m0
	s_mov_b32 m0, s20
	s_nop 0
	global_load_lds_dwordx4 v207, s[58:59]
	s_mov_b32 m0, s61
	s_setprio 0
	v_mfma_f32_32x32x16_bf16 v[16:31], v[68:71], v[148:151], v[16:31]
	v_mfma_f32_32x32x16_bf16 v[16:31], v[72:75], v[152:155], v[16:31]
	v_mfma_f32_32x32x16_bf16 v[16:31], v[76:79], v[156:159], v[16:31]
	s_waitcnt lgkmcnt(0)
; __device__ __forceinline__ void qkt_k(f32x16& p0, f32x16& p1, const char* Ks, const bf16x8* kf, const bf16x8* qr, int r32, int hi, int mapB) {
;   p0 = f32x16{}; p1 = f32x16{};
;   p0 = __builtin_amdgcn_mfma_f32_32x32x16_bf16(kf[0], qr[0], p0, 0, 0, 0);
;   p1 = __builtin_amdgcn_mfma_f32_32x32x16_bf16(kf[1], qr[0], p1, 0, 0, 0);
; #pragma unroll
;   for (int d0 = 1; d0 < 4; ++d0) { const int cb = (d0 * 16 + hi * 8) * 2 + mapB;
;     bf16x8 b0 = *reinterpret_cast<const bf16x8*>(Ks + KSWZ(r32, cb));
;     bf16x8 b1 = *reinterpret_cast<const bf16x8*>(Ks + KSWZ(32 + r32, cb));
;     p0 = __builtin_amdgcn_mfma_f32_32x32x16_bf16(b0, qr[d0], p0, 0, 0, 0);
;     p1 = __builtin_amdgcn_mfma_f32_32x32x16_bf16(b1, qr[d0], p1, 0, 0, 0); }
; }
	v_mfma_f32_32x32x16_bf16 v[0:15], v[64:67], v[80:83], v[0:15]
	s_add_u32 s58, s12, 0x90400
	s_addc_u32 s59, s13, 0
	s_addk_i32 s60, 0x6000
	s_setprio 3
	s_mov_b32 s20, m0
	s_mov_b32 m0, s60
	s_nop 0
	global_load_lds_dwordx4 v207, s[58:59]
	s_mov_b32 m0, s20
	s_setprio 0
	ds_read_b128 v[64:67], v160 offset:32768
	ds_read_b128 v[80:83], v160 offset:40960
	v_mfma_f32_32x32x16_bf16 v[0:15], v[68:71], v[84:87], v[0:15]
	v_mfma_f32_32x32x16_bf16 v[0:15], v[72:75], v[88:91], v[0:15]
	v_mfma_f32_32x32x16_bf16 v[0:15], v[76:79], v[92:95], v[0:15]
	s_setprio 1
	v_add_u32_e32 v148, s27, v164
	ds_read_b128 v[144:147], v148
	ds_read_b128 v[148:151], v148 offset:8192
	v_exp_f32_e32 v96, v96
	v_exp_f32_e32 v97, v97
	v_exp_f32_e32 v98, v98
	v_exp_f32_e32 v99, v99
	s_waitcnt lgkmcnt(2)
	v_mfma_f32_32x32x16_bf16 v[80:95], v[80:83], v[140:143], 0
	v_exp_f32_e32 v100, v100
	v_exp_f32_e32 v101, v101
	v_exp_f32_e32 v102, v102
	v_exp_f32_e32 v103, v103
	v_exp_f32_e32 v104, v104
	v_exp_f32_e32 v105, v105
	v_exp_f32_e32 v106, v106
	v_mfma_f32_32x32x16_bf16 v[64:79], v[64:67], v[140:143], 0
	v_add_u32_e32 v156, s27, v163
	ds_read_b128 v[152:155], v156
	ds_read_b128 v[156:159], v156 offset:8192
	v_exp_f32_e32 v107, v107
	v_exp_f32_e32 v161, v109
	v_exp_f32_e32 v172, v110
	v_exp_f32_e32 v173, v111
	v_exp_f32_e32 v112, v112
	v_exp_f32_e32 v113, v113
	v_exp_f32_e32 v114, v114
	s_waitcnt lgkmcnt(2)
	v_mfma_f32_32x32x16_bf16 v[80:95], v[148:151], v[136:139], v[80:95]
	v_exp_f32_e32 v115, v115
	v_exp_f32_e32 v116, v116
	v_exp_f32_e32 v117, v117
	v_exp_f32_e32 v118, v118
	v_exp_f32_e32 v119, v119
	v_exp_f32_e32 v120, v120
	v_exp_f32_e32 v121, v121
	v_mfma_f32_32x32x16_bf16 v[64:79], v[144:147], v[136:139], v[64:79]
	v_add_u32_e32 v148, s27, v162
	ds_read_b128 v[144:147], v148
	ds_read_b128 v[148:151], v148 offset:8192
	v_exp_f32_e32 v122, v122
	v_exp_f32_e32 v123, v123
	v_exp_f32_e32 v124, v124
	v_exp_f32_e32 v125, v125
	v_exp_f32_e32 v126, v126
	v_exp_f32_e32 v127, v127
	v_cvt_pk_bf16_f32 v109, v98, v99
	s_waitcnt lgkmcnt(2)
	v_mfma_f32_32x32x16_bf16 v[80:95], v[156:159], v[132:135], v[80:95]
	v_cvt_pk_bf16_f32 v110, v100, v101
	v_cvt_pk_bf16_f32 v111, v102, v103
	v_exp_f32_e32 v238, v108
	v_add_f32_e32 v108, 0, v96
	v_add_f32_e32 v108, v97, v108
	v_add_f32_e32 v108, v98, v108
	v_add_f32_e32 v108, v99, v108
	v_add_f32_e32 v108, v100, v108
	v_add_f32_e32 v108, v101, v108
	v_add_f32_e32 v108, v102, v108
	v_add_f32_e32 v108, v103, v108
	v_add_f32_e32 v108, v104, v108
	v_add_f32_e32 v108, v105, v108
	v_mfma_f32_32x32x16_bf16 v[64:79], v[152:155], v[132:135], v[64:79]
	v_add_u32_e32 v160, s21, v208
	ds_read_b64_tr_b16 v[156:157], v160 offset:0
	ds_read_b64_tr_b16 v[158:159], v160 offset:0x800
	ds_read_b64_tr_b16 v[152:153], v160 offset:0x1000
	ds_read_b64_tr_b16 v[154:155], v160 offset:0x1800
	v_add_f32_e32 v108, v106, v108
	v_add_f32_e32 v108, v107, v108
	v_add_f32_e32 v108, v238, v108
	v_add_f32_e32 v108, v161, v108
	v_add_f32_e32 v108, v172, v108
	v_add_f32_e32 v108, v173, v108
	v_add_f32_e32 v108, v112, v108
	v_add_f32_e32 v108, v113, v108
	v_add_f32_e32 v108, v114, v108
	v_add_f32_e32 v108, v115, v108
	v_add_f32_e32 v108, v116, v108
	v_add_f32_e32 v108, v117, v108
	v_add_f32_e32 v108, v118, v108
	v_add_f32_e32 v108, v119, v108
	s_waitcnt lgkmcnt(4)
	v_mfma_f32_32x32x16_bf16 v[80:95], v[148:151], v[128:131], v[80:95]
	ds_read_b64_tr_b16 v[148:149], v160 offset:0x2000
	ds_read_b64_tr_b16 v[150:151], v160 offset:0x2800
	v_add_f32_e32 v108, v120, v108
	v_add_f32_e32 v108, v121, v108
	v_add_f32_e32 v108, v122, v108
	v_add_f32_e32 v108, v123, v108
	v_add_f32_e32 v108, v124, v108
	v_add_f32_e32 v108, v125, v108
	v_add_f32_e32 v108, v126, v108
	v_add_f32_e32 v108, v127, v108
	v_add_f32_e32 v171, v171, v108
	v_cvt_pk_bf16_f32 v108, v96, v97
	v_cvt_pk_bf16_f32 v104, v104, v105
	v_cvt_pk_bf16_f32 v105, v106, v107
	v_mfma_f32_32x32x16_bf16 v[64:79], v[144:147], v[128:131], v[64:79]
	ds_read_b64_tr_b16 v[144:145], v160 offset:0x3000
	ds_read_b64_tr_b16 v[146:147], v160 offset:0x3800
	v_cvt_pk_bf16_f32 v106, v238, v161
	v_cvt_pk_bf16_f32 v107, v172, v173
	v_cvt_pk_bf16_f32 v100, v112, v113
	v_cvt_pk_bf16_f32 v101, v114, v115
	v_cvt_pk_bf16_f32 v102, v116, v117
	v_cvt_pk_bf16_f32 v103, v118, v119
	v_cvt_pk_bf16_f32 v96, v120, v121
	v_cvt_pk_bf16_f32 v97, v122, v123
	v_cvt_pk_bf16_f32 v98, v124, v125
	v_cvt_pk_bf16_f32 v99, v126, v127
	s_setprio 0
	s_add_i32 s18, s18, 2
	s_waitcnt vmcnt(0)
	s_add_u32 s12, s12, 0xc0000
	s_addc_u32 s13, s13, 0
	s_cmp_ge_u32 s18, s56
	s_mov_b32 s20, s26
	s_barrier
	s_cbranch_scc0 .LBB0_355
; #define LANDED() do { asm volatile("s_waitcnt vmcnt(0)" ::: "memory"); __syncthreads(); } while (0)
; #define BLK_XK(N0, N1, P0, P1, alP, t) do { SBAR(); __builtin_amdgcn_s_setprio(1); \
;     if constexpr (SH) qkt(N0, N1, KBUF((t) & 3), qr, r32, hi, mapB); else qkt_k(N0, N1, KBUF((t) & 3), kf, qr, r32, hi, mapB); \
;     if constexpr (!SH) v_frag_read<0>(vfa, VBUF(((t) - 1) & 3)); \
;     finishSM<SH>(P0, P1, alP, l_reg, pa0, pa1, pa2, pa3); __builtin_amdgcn_s_setprio(0); SBAR(); } while (0)
; template <bool SH> __device__ __forceinline__ void attn_unit(bf16_t* __restrict__ proj, int tok0, int kv0, int seq, int h, float lam, float oscale, const float* __restrict__ subg, char* lds, bool dry) {
;     ...
;     BLK_Y1(pB0, pB1, mnB, alB, NT - 4, NT - 1); BLK_XK(pA0, pA1, pB0, pB1, alB, NT - 2); LANDED();
	s_waitcnt lgkmcnt(0)
	v_or_b32_e32 v112, 0x2000, v209
	v_add_u32_e32 v173, v167, v112
	v_add_u32_e32 v172, v168, v112
	v_add_u32_e32 v168, v169, v112
	v_add_u32_e32 v167, v170, v112
	ds_read_b64_tr_b16 v[112:113], v208 offset:0x200
	ds_read_b64_tr_b16 v[114:115], v208 offset:0xa00
	ds_read_b64_tr_b16 v[116:117], v208 offset:0x1200
	ds_read_b64_tr_b16 v[118:119], v208 offset:0x1a00
	ds_read_b64_tr_b16 v[120:121], v208 offset:0x2200
	ds_read_b64_tr_b16 v[122:123], v208 offset:0x2a00
	ds_read_b64_tr_b16 v[124:125], v208 offset:0x3200
	ds_read_b64_tr_b16 v[126:127], v208 offset:0x3a00
	v_mfma_f32_32x32x16_bf16 v[48:63], v[108:111], v[156:159], v[48:63]
	s_add_i32 s12, s56, -1
	s_mul_i32 s21, s12, 0x60000
	s_mul_hi_u32 s20, s12, 0x60000
	s_add_u32 s12, s10, s21
	s_addc_u32 s13, s11, s20
	s_add_i32 s10, 0, 0x18000
	s_add_i32 s11, s17, s10
	v_mfma_f32_32x32x16_bf16 v[48:63], v[104:107], v[152:155], v[48:63]
	s_setprio 3
	s_mov_b32 s18, m0
	s_mov_b32 m0, s11
	s_nop 0
	global_load_lds_dwordx4 v166, s[12:13]
	s_mov_b32 m0, s18
	s_setprio 0
	s_add_u32 s18, s12, 0xfffe8000
	s_addc_u32 s19, s13, -1
	s_add_i32 s11, s5, 0x17000
	s_setprio 3
	s_mov_b32 s26, m0
	s_mov_b32 m0, s11
	s_nop 0
	global_load_lds_dwordx4 v166, s[18:19]
	s_mov_b32 m0, s26
	s_setprio 0
	v_mfma_f32_32x32x16_bf16 v[48:63], v[100:103], v[148:151], v[48:63]
	v_mfma_f32_32x32x16_bf16 v[48:63], v[96:99], v[144:147], v[48:63]
	s_waitcnt lgkmcnt(0)
	ds_read_b64_tr_b16 v[144:145], v208 offset:0x400
	ds_read_b64_tr_b16 v[146:147], v208 offset:0xc00
	ds_read_b64_tr_b16 v[148:149], v208 offset:0x1400
	ds_read_b64_tr_b16 v[150:151], v208 offset:0x1c00
	ds_read_b64_tr_b16 v[152:153], v208 offset:0x2400
	ds_read_b64_tr_b16 v[154:155], v208 offset:0x2c00
	ds_read_b64_tr_b16 v[156:157], v208 offset:0x3400
	ds_read_b64_tr_b16 v[158:159], v208 offset:0x3c00
	v_mfma_f32_32x32x16_bf16 v[32:47], v[108:111], v[112:115], v[32:47]
	s_add_u32 s18, s12, 0x30000
	s_addc_u32 s19, s13, 0
	s_add_i32 s11, s5, 0x1a000
	s_setprio 3
	s_mov_b32 s26, m0
	s_mov_b32 m0, s11
	s_nop 0
	global_load_lds_dwordx4 v166, s[18:19]
	s_mov_b32 m0, s26
	s_setprio 0
	s_add_u32 s12, s12, 0x18000
	s_addc_u32 s13, s13, 0
	s_add_i32 s11, s5, 0x19000
	v_mfma_f32_32x32x16_bf16 v[32:47], v[104:107], v[116:119], v[32:47]
	s_setprio 3
	s_mov_b32 s18, m0
	s_mov_b32 m0, s11
	s_nop 0
	global_load_lds_dwordx4 v166, s[12:13]
	s_mov_b32 m0, s18
	s_setprio 0
	v_mfma_f32_32x32x16_bf16 v[32:47], v[100:103], v[120:123], v[32:47]
	v_mfma_f32_32x32x16_bf16 v[32:47], v[96:99], v[124:127], v[32:47]
	s_waitcnt lgkmcnt(0)
	ds_read_b64_tr_b16 v[112:113], v208 offset:0x600
	ds_read_b64_tr_b16 v[114:115], v208 offset:0xe00
	ds_read_b64_tr_b16 v[116:117], v208 offset:0x1600
	ds_read_b64_tr_b16 v[118:119], v208 offset:0x1e00
	ds_read_b64_tr_b16 v[120:121], v208 offset:0x2600
	ds_read_b64_tr_b16 v[122:123], v208 offset:0x2e00
	ds_read_b64_tr_b16 v[124:125], v208 offset:0x3600
	ds_read_b64_tr_b16 v[126:127], v208 offset:0x3e00
	v_mfma_f32_32x32x16_bf16 v[16:31], v[108:111], v[144:147], v[16:31]
	s_add_u32 s12, s8, s21
	s_addc_u32 s13, s9, s20
	s_add_i32 s8, 0, 0x1c000
	s_add_i32 s17, s17, s8
	s_setprio 3
	s_mov_b32 s9, m0
	s_mov_b32 m0, s17
	s_nop 0
	global_load_lds_dwordx4 v207, s[12:13]
	s_mov_b32 m0, s9
	s_setprio 0
	v_mfma_f32_32x32x16_bf16 v[16:31], v[104:107], v[148:151], v[16:31]
	v_mfma_f32_32x32x16_bf16 v[16:31], v[100:103], v[152:155], v[16:31]
	v_mfma_f32_32x32x16_bf16 v[16:31], v[96:99], v[156:159], v[16:31]
	s_waitcnt lgkmcnt(0)
	v_mfma_f32_32x32x16_bf16 v[0:15], v[108:111], v[112:115], v[0:15]
	s_add_u32 s12, s12, 0x30000
	s_addc_u32 s13, s13, 0
	s_add_i32 s9, s5, 0x1e000
	s_setprio 3
	s_mov_b32 s11, m0
	s_mov_b32 m0, s9
	s_nop 0
	global_load_lds_dwordx4 v207, s[12:13]
	s_mov_b32 m0, s11
	s_setprio 0
	s_add_i32 s9, 0, 0x10000
	v_mfma_f32_32x32x16_bf16 v[0:15], v[104:107], v[116:119], v[0:15]
	v_add_u32_e32 v104, s9, v173
	v_mfma_f32_32x32x16_bf16 v[0:15], v[100:103], v[120:123], v[0:15]
	v_add_u32_e32 v100, s9, v165
	ds_read_b128 v[100:103], v100
	ds_read_b128 v[112:115], v104
	v_mfma_f32_32x32x16_bf16 v[0:15], v[96:99], v[124:127], v[0:15]
	s_setprio 1
	v_add_u32_e32 v144, s9, v164
	ds_read_b128 v[144:147], v144
	s_waitcnt lgkmcnt(2)
	v_mfma_f32_32x32x16_bf16 v[96:111], v[100:103], v[140:143], 0
	v_add_u32_e32 v148, s9, v172
	ds_read_b128 v[148:151], v148
	v_exp_f32_e32 v64, v64
	v_exp_f32_e32 v65, v65
	v_exp_f32_e32 v66, v66
	v_exp_f32_e32 v67, v67
	v_exp_f32_e32 v68, v68
	s_waitcnt lgkmcnt(1)
	v_mfma_f32_32x32x16_bf16 v[96:111], v[144:147], v[136:139], v[96:111]
	v_add_u32_e32 v144, s9, v163
	ds_read_b128 v[144:147], v144
	v_exp_f32_e32 v69, v69
	v_exp_f32_e32 v70, v70
	v_exp_f32_e32 v71, v71
	v_exp_f32_e32 v72, v72
	v_exp_f32_e32 v73, v73
	v_mfma_f32_32x32x16_bf16 v[112:127], v[112:115], v[140:143], 0
	v_exp_f32_e32 v74, v74
	v_exp_f32_e32 v75, v75
	v_exp_f32_e32 v76, v76
	v_exp_f32_e32 v77, v77
	v_exp_f32_e32 v78, v78
	v_exp_f32_e32 v79, v79
	v_exp_f32_e32 v80, v80
	s_waitcnt lgkmcnt(1)
	v_mfma_f32_32x32x16_bf16 v[112:127], v[148:151], v[136:139], v[112:127]
	v_add_u32_e32 v148, s9, v168
	ds_read_b128 v[148:151], v148
	v_exp_f32_e32 v81, v81
	v_exp_f32_e32 v82, v82
	v_exp_f32_e32 v83, v83
	v_exp_f32_e32 v84, v84
	v_exp_f32_e32 v85, v85
	s_waitcnt lgkmcnt(1)
	v_mfma_f32_32x32x16_bf16 v[96:111], v[144:147], v[132:135], v[96:111]
	v_add_u32_e32 v144, s9, v162
	ds_read_b128 v[144:147], v144
	v_exp_f32_e32 v86, v86
	v_exp_f32_e32 v87, v87
	v_exp_f32_e32 v88, v88
	v_exp_f32_e32 v89, v89
	v_exp_f32_e32 v90, v90
	s_waitcnt lgkmcnt(1)
; #define SBAR() __builtin_amdgcn_sched_barrier(0)
; #define LANDED() do { asm volatile("s_waitcnt vmcnt(0)" ::: "memory"); __syncthreads(); } while (0)
; #define BLK_X(N0, N1, P0, P1, alP, t) do { SBAR(); __builtin_amdgcn_s_setprio(1); qkt(N0, N1, KBUF((t) & 3), qr, r32, hi, mapB); \
;     if constexpr (!SH) v_frag_read<0>(vfa, VBUF(((t) - 1) & 3)); \
;     finishSM<SH>(P0, P1, alP, l_reg, pa0, pa1, pa2, pa3); __builtin_amdgcn_s_setprio(0); SBAR(); } while (0)
; #define BLK_XK(N0, N1, P0, P1, alP, t) do { SBAR(); __builtin_amdgcn_s_setprio(1); \
;     if constexpr (SH) qkt(N0, N1, KBUF((t) & 3), qr, r32, hi, mapB); else qkt_k(N0, N1, KBUF((t) & 3), kf, qr, r32, hi, mapB); \
;     if constexpr (!SH) v_frag_read<0>(vfa, VBUF(((t) - 1) & 3)); \
;     finishSM<SH>(P0, P1, alP, l_reg, pa0, pa1, pa2, pa3); __builtin_amdgcn_s_setprio(0); SBAR(); } while (0)
; #define BLK_Y(C0, C1, mnC, alC, t) do { if constexpr (SH) pv_d0(o, VBUF((t) & 3), pa0, pa1, pa2, pa3); else pv_d0_pipe<true>(o, VBUF((t) & 3), pa0, pa1, pa2, pa3, vfa); partialSM<SH>(C0, C1, m_reg, mnC, alC); RESC(alC); } while (0)
; template <bool PRE> __device__ __forceinline__ void pv_d0_pipe(f32x16* o, int vb, bf16x8 pa0, bf16x8 pa1, bf16x8 pa2, bf16x8 pa3, VFrag& fa) {
;   VFrag fb;
;   if constexpr (!PRE) v_frag_read<0>(fa, vb);
;   asm volatile("s_waitcnt lgkmcnt(0)" ::: "memory"); SBAR();
;   v_frag_read<1>(fb, vb); SBAR(); v_frag_mma(o[0], fa, pa0, pa1, pa2, pa3); SBAR(); asm volatile("s_waitcnt lgkmcnt(0)" ::: "memory"); SBAR();
;   v_frag_read<2>(fa, vb); SBAR(); v_frag_mma(o[1], fb, pa0, pa1, pa2, pa3); SBAR(); asm volatile("s_waitcnt lgkmcnt(0)" ::: "memory"); SBAR();
;   v_frag_read<3>(fb, vb); SBAR(); v_frag_mma(o[2], fa, pa0, pa1, pa2, pa3); SBAR(); asm volatile("s_waitcnt lgkmcnt(0)" ::: "memory"); SBAR();
;   v_frag_mma(o[3], fb, pa0, pa1, pa2, pa3);
; }
; template <bool SH> __device__ __forceinline__ void attn_unit(bf16_t* __restrict__ proj, int tok0, int kv0, int seq, int h, float lam, float oscale, const float* __restrict__ subg, char* lds, bool dry) {
;     ...
;     BLK_Y1(pB0, pB1, mnB, alB, NT - 4, NT - 1); BLK_XK(pA0, pA1, pB0, pB1, alB, NT - 2); LANDED();
;     BLK_Y(pA0, pA1, mnA, alA, NT - 3); BLK_X(pB0, pB1, pA0, pA1, alA, NT - 1);
	v_mfma_f32_32x32x16_bf16 v[112:127], v[148:151], v[132:135], v[112:127]
	v_add_u32_e32 v148, s9, v167
	ds_read_b128 v[148:151], v148
	s_add_i32 s9, 0, 0xc000
	v_exp_f32_e32 v91, v91
	v_exp_f32_e32 v92, v92
	v_exp_f32_e32 v93, v93
	v_exp_f32_e32 v94, v94
	s_waitcnt lgkmcnt(1)
	v_mfma_f32_32x32x16_bf16 v[96:111], v[144:147], v[128:131], v[96:111]
	v_add_f32_e32 v144, 0, v64
	v_add_f32_e32 v144, v65, v144
	v_add_f32_e32 v144, v66, v144
	v_add_f32_e32 v144, v67, v144
	v_add_f32_e32 v144, v68, v144
	v_add_f32_e32 v144, v69, v144
	v_add_f32_e32 v144, v70, v144
	v_add_f32_e32 v144, v71, v144
	v_add_f32_e32 v144, v72, v144
	v_add_f32_e32 v144, v73, v144
	v_add_f32_e32 v144, v74, v144
	v_add_f32_e32 v144, v75, v144
	v_add_f32_e32 v144, v76, v144
	v_add_f32_e32 v144, v77, v144
	v_add_f32_e32 v144, v78, v144
	v_add_f32_e32 v144, v79, v144
	v_add_f32_e32 v144, v80, v144
	v_add_f32_e32 v144, v81, v144
	v_add_f32_e32 v144, v82, v144
	v_add_f32_e32 v144, v83, v144
	v_add_f32_e32 v144, v84, v144
	v_add_f32_e32 v144, v85, v144
	v_add_u32_e32 v145, s9, v206
	ds_read_b64_tr_b16 v[146:147], v145 offset:0
	v_add_f32_e32 v144, v86, v144
	s_waitcnt lgkmcnt(0)
	v_mfma_f32_32x32x16_bf16 v[112:127], v[148:151], v[128:131], v[112:127]
	ds_read_b64_tr_b16 v[148:149], v145 offset:0x800
	v_add_f32_e32 v144, v87, v144
	ds_read_b64_tr_b16 v[150:151], v145 offset:0x1000
	v_add_f32_e32 v144, v88, v144
	ds_read_b64_tr_b16 v[152:153], v145 offset:0x1800
	v_add_f32_e32 v144, v89, v144
	ds_read_b64_tr_b16 v[154:155], v145 offset:0x2000
	v_add_f32_e32 v144, v90, v144
	ds_read_b64_tr_b16 v[156:157], v145 offset:0x2800
	v_exp_f32_e32 v95, v95
	v_add_f32_e32 v144, v91, v144
	ds_read_b64_tr_b16 v[174:175], v145 offset:0x3000
	v_add_f32_e32 v144, v92, v144
	ds_read_b64_tr_b16 v[176:177], v145 offset:0x3800
	v_add_f32_e32 v144, v93, v144
	v_add_f32_e32 v144, v94, v144
	v_add_f32_e32 v144, v95, v144
	v_add_f32_e32 v144, v171, v144
	v_cvt_pk_bf16_f32 v64, v64, v65
	v_cvt_pk_bf16_f32 v65, v66, v67
	v_cvt_pk_bf16_f32 v66, v68, v69
	v_cvt_pk_bf16_f32 v67, v70, v71
	v_cvt_pk_bf16_f32 v68, v72, v73
	v_cvt_pk_bf16_f32 v69, v74, v75
	v_cvt_pk_bf16_f32 v70, v76, v77
	v_cvt_pk_bf16_f32 v71, v78, v79
	v_cvt_pk_bf16_f32 v72, v80, v81
	v_cvt_pk_bf16_f32 v73, v82, v83
	v_cvt_pk_bf16_f32 v74, v84, v85
	v_cvt_pk_bf16_f32 v75, v86, v87
	v_cvt_pk_bf16_f32 v76, v88, v89
	v_cvt_pk_bf16_f32 v77, v90, v91
	v_cvt_pk_bf16_f32 v78, v92, v93
	v_cvt_pk_bf16_f32 v79, v94, v95
	s_setprio 0
	s_waitcnt vmcnt(0)
	s_barrier
	s_waitcnt lgkmcnt(0)
	ds_read_b64_tr_b16 v[80:81], v145 offset:0x200
	ds_read_b64_tr_b16 v[82:83], v145 offset:0xa00
	ds_read_b64_tr_b16 v[84:85], v145 offset:0x1200
	ds_read_b64_tr_b16 v[86:87], v145 offset:0x1a00
	ds_read_b64_tr_b16 v[88:89], v145 offset:0x2200
	ds_read_b64_tr_b16 v[90:91], v145 offset:0x2a00
	ds_read_b64_tr_b16 v[92:93], v145 offset:0x3200
	ds_read_b64_tr_b16 v[94:95], v145 offset:0x3a00
	v_mfma_f32_32x32x16_bf16 v[48:63], v[64:67], v[146:149], v[48:63]
	v_mfma_f32_32x32x16_bf16 v[48:63], v[68:71], v[150:153], v[48:63]
	v_mfma_f32_32x32x16_bf16 v[48:63], v[72:75], v[154:157], v[48:63]
	v_mfma_f32_32x32x16_bf16 v[48:63], v[76:79], v[174:177], v[48:63]
	s_waitcnt lgkmcnt(0)
	ds_read_b64_tr_b16 v[146:147], v145 offset:0x400
	ds_read_b64_tr_b16 v[148:149], v145 offset:0xc00
	ds_read_b64_tr_b16 v[150:151], v145 offset:0x1400
	ds_read_b64_tr_b16 v[152:153], v145 offset:0x1c00
	ds_read_b64_tr_b16 v[154:155], v145 offset:0x2400
	ds_read_b64_tr_b16 v[156:157], v145 offset:0x2c00
	ds_read_b64_tr_b16 v[174:175], v145 offset:0x3400
	ds_read_b64_tr_b16 v[176:177], v145 offset:0x3c00
	v_mfma_f32_32x32x16_bf16 v[32:47], v[64:67], v[80:83], v[32:47]
	v_mfma_f32_32x32x16_bf16 v[32:47], v[68:71], v[84:87], v[32:47]
	v_mfma_f32_32x32x16_bf16 v[32:47], v[72:75], v[88:91], v[32:47]
	v_mfma_f32_32x32x16_bf16 v[32:47], v[76:79], v[92:95], v[32:47]
	s_waitcnt lgkmcnt(0)
	ds_read_b64_tr_b16 v[80:81], v145 offset:0x600
	ds_read_b64_tr_b16 v[82:83], v145 offset:0xe00
	ds_read_b64_tr_b16 v[84:85], v145 offset:0x1600
	ds_read_b64_tr_b16 v[86:87], v145 offset:0x1e00
	ds_read_b64_tr_b16 v[88:89], v145 offset:0x2600
	ds_read_b64_tr_b16 v[90:91], v145 offset:0x2e00
	ds_read_b64_tr_b16 v[92:93], v145 offset:0x3600
	ds_read_b64_tr_b16 v[94:95], v145 offset:0x3e00
	v_mfma_f32_32x32x16_bf16 v[16:31], v[64:67], v[146:149], v[16:31]
	v_mfma_f32_32x32x16_bf16 v[16:31], v[68:71], v[150:153], v[16:31]
	v_mfma_f32_32x32x16_bf16 v[16:31], v[72:75], v[154:157], v[16:31]
	v_mfma_f32_32x32x16_bf16 v[16:31], v[76:79], v[174:177], v[16:31]
	s_waitcnt lgkmcnt(0)
	v_mfma_f32_32x32x16_bf16 v[0:15], v[64:67], v[80:83], v[0:15]
	v_mfma_f32_32x32x16_bf16 v[0:15], v[68:71], v[84:87], v[0:15]
	v_mfma_f32_32x32x16_bf16 v[0:15], v[72:75], v[88:91], v[0:15]
	v_mfma_f32_32x32x16_bf16 v[0:15], v[76:79], v[92:95], v[0:15]
	s_setprio 1
	v_add_u32_e32 v64, s10, v165
	ds_read_b128 v[64:67], v64
	v_add_u32_e32 v68, s10, v173
	ds_read_b128 v[80:83], v68
	v_add_u32_e32 v145, s10, v164
	ds_read_b128 v[146:149], v145
	v_add_u32_e32 v145, s10, v172
	ds_read_b128 v[150:153], v145
	v_add_u32_e32 v145, s10, v163
	s_add_i32 s9, 0, 0x14000
	s_waitcnt lgkmcnt(3)
	v_mfma_f32_32x32x16_bf16 v[64:79], v[64:67], v[140:143], 0
	v_exp_f32_e32 v154, v100
	v_exp_f32_e32 v100, v116
	v_exp_f32_e32 v156, v101
	v_exp_f32_e32 v158, v102
	v_exp_f32_e32 v102, v118
	v_exp_f32_e32 v116, v119
	v_exp_f32_e32 v118, v120
	s_waitcnt lgkmcnt(2)
	v_mfma_f32_32x32x16_bf16 v[80:95], v[80:83], v[140:143], 0
	v_exp_f32_e32 v164, v105
	v_exp_f32_e32 v166, v106
	v_exp_f32_e32 v106, v122
	v_exp_f32_e32 v170, v107
	v_exp_f32_e32 v120, v123
	v_exp_f32_e32 v172, v108
	v_exp_f32_e32 v108, v124
	s_waitcnt lgkmcnt(1)
; #define BLK_X(N0, N1, P0, P1, alP, t) do { SBAR(); __builtin_amdgcn_s_setprio(1); qkt(N0, N1, KBUF((t) & 3), qr, r32, hi, mapB); \
;     if constexpr (!SH) v_frag_read<0>(vfa, VBUF(((t) - 1) & 3)); \
;     finishSM<SH>(P0, P1, alP, l_reg, pa0, pa1, pa2, pa3); __builtin_amdgcn_s_setprio(0); SBAR(); } while (0)
; #define BLK_Y(C0, C1, mnC, alC, t) do { if constexpr (SH) pv_d0(o, VBUF((t) & 3), pa0, pa1, pa2, pa3); else pv_d0_pipe<true>(o, VBUF((t) & 3), pa0, pa1, pa2, pa3, vfa); partialSM<SH>(C0, C1, m_reg, mnC, alC); RESC(alC); } while (0)
; template <bool SH> __device__ __forceinline__ void attn_unit(bf16_t* __restrict__ proj, int tok0, int kv0, int seq, int h, float lam, float oscale, const float* __restrict__ subg, char* lds, bool dry) {
;     ...
;     BLK_Y(pA0, pA1, mnA, alA, NT - 3); BLK_X(pB0, pB1, pA0, pA1, alA, NT - 1);
;     BLK_Y(pB0, pB1, mnB, alB, NT - 2);
	v_mfma_f32_32x32x16_bf16 v[64:79], v[146:149], v[136:139], v[64:79]
	ds_read_b128 v[146:149], v145
	v_add_u32_e32 v145, s10, v168
	v_exp_f32_e32 v168, v104
	v_exp_f32_e32 v104, v121
	v_exp_f32_e32 v174, v109
	v_exp_f32_e32 v122, v125
	v_exp_f32_e32 v176, v110
	s_waitcnt lgkmcnt(1)
	v_mfma_f32_32x32x16_bf16 v[80:95], v[150:153], v[136:139], v[80:95]
	ds_read_b128 v[150:153], v145
	v_add_u32_e32 v145, s10, v162
	v_exp_f32_e32 v162, v103
	v_exp_f32_e32 v110, v126
	v_exp_f32_e32 v126, v111
	v_exp_f32_e32 v124, v127
	v_cvt_pk_bf16_f32 v226, v154, v156
	s_waitcnt lgkmcnt(1)
	v_mfma_f32_32x32x16_bf16 v[64:79], v[146:149], v[132:135], v[64:79]
	ds_read_b128 v[146:149], v145
	v_add_u32_e32 v145, s10, v167
	v_cvt_pk_bf16_f32 v227, v158, v162
	v_cvt_pk_bf16_f32 v228, v168, v164
	v_cvt_pk_bf16_f32 v229, v166, v170
	v_cvt_pk_bf16_f32 v230, v172, v174
	v_cvt_pk_bf16_f32 v231, v176, v126
	s_waitcnt lgkmcnt(1)
	v_mfma_f32_32x32x16_bf16 v[80:95], v[150:153], v[132:135], v[80:95]
	ds_read_b128 v[150:153], v145
	v_add_u32_e32 v145, s9, v206
	ds_read_b64_tr_b16 v[194:195], v145 offset:0
	ds_read_b64_tr_b16 v[196:197], v145 offset:0x800
	ds_read_b64_tr_b16 v[212:213], v145 offset:0x1000
	ds_read_b64_tr_b16 v[214:215], v145 offset:0x1800
	ds_read_b64_tr_b16 v[216:217], v145 offset:0x2000
	s_waitcnt lgkmcnt(0)
	v_mfma_f32_32x32x16_bf16 v[80:95], v[150:153], v[128:131], v[80:95]
	ds_read_b64_tr_b16 v[218:219], v145 offset:0x2800
	ds_read_b64_tr_b16 v[220:221], v145 offset:0x3000
	v_exp_f32_e32 v150, v98
	v_exp_f32_e32 v98, v114
	v_exp_f32_e32 v152, v99
	v_exp_f32_e32 v114, v117
	ds_read_b64_tr_b16 v[222:223], v145 offset:0x3800
	v_mfma_f32_32x32x16_bf16 v[64:79], v[146:149], v[128:131], v[64:79]
	v_exp_f32_e32 v147, v96
	v_exp_f32_e32 v146, v112
	v_exp_f32_e32 v148, v97
	v_exp_f32_e32 v96, v113
	v_exp_f32_e32 v112, v115
	v_add_f32_e32 v160, 0, v147
	v_cvt_pk_bf16_f32 v224, v147, v148
	v_cvt_pk_bf16_f32 v225, v150, v152
	v_cvt_pk_bf16_f32 v232, v146, v96
	v_cvt_pk_bf16_f32 v233, v98, v112
	v_cvt_pk_bf16_f32 v234, v100, v114
	v_cvt_pk_bf16_f32 v235, v102, v116
	v_cvt_pk_bf16_f32 v236, v118, v104
	v_cvt_pk_bf16_f32 v237, v106, v120
	v_cvt_pk_bf16_f32 v238, v108, v122
	v_cvt_pk_bf16_f32 v239, v110, v124
	s_setprio 0
	s_waitcnt lgkmcnt(0)
	ds_read_b64_tr_b16 v[240:241], v145 offset:0x200
	ds_read_b64_tr_b16 v[242:243], v145 offset:0xa00
	ds_read_b64_tr_b16 v[244:245], v145 offset:0x1200
	ds_read_b64_tr_b16 v[246:247], v145 offset:0x1a00
	ds_read_b64_tr_b16 v[248:249], v145 offset:0x2200
	ds_read_b64_tr_b16 v[250:251], v145 offset:0x2a00
	ds_read_b64_tr_b16 v[186:187], v145 offset:0x3200
	ds_read_b64_tr_b16 v[188:189], v145 offset:0x3a00
	v_mfma_f32_32x32x16_bf16 v[48:63], v[224:227], v[194:197], v[48:63]
	v_mfma_f32_32x32x16_bf16 v[48:63], v[228:231], v[212:215], v[48:63]
	v_mfma_f32_32x32x16_bf16 v[48:63], v[232:235], v[216:219], v[48:63]
	v_mfma_f32_32x32x16_bf16 v[48:63], v[236:239], v[220:223], v[48:63]
	s_waitcnt lgkmcnt(0)
	ds_read_b64_tr_b16 v[194:195], v145 offset:0x400
	ds_read_b64_tr_b16 v[196:197], v145 offset:0xc00
	ds_read_b64_tr_b16 v[212:213], v145 offset:0x1400
	ds_read_b64_tr_b16 v[214:215], v145 offset:0x1c00
	ds_read_b64_tr_b16 v[216:217], v145 offset:0x2400
	ds_read_b64_tr_b16 v[218:219], v145 offset:0x2c00
	ds_read_b64_tr_b16 v[220:221], v145 offset:0x3400
	ds_read_b64_tr_b16 v[222:223], v145 offset:0x3c00
	v_mfma_f32_32x32x16_bf16 v[32:47], v[224:227], v[240:243], v[32:47]
	v_mfma_f32_32x32x16_bf16 v[32:47], v[228:231], v[244:247], v[32:47]
	v_mfma_f32_32x32x16_bf16 v[32:47], v[232:235], v[248:251], v[32:47]
	v_mfma_f32_32x32x16_bf16 v[32:47], v[236:239], v[186:189], v[32:47]
	s_waitcnt lgkmcnt(0)
	ds_read_b64_tr_b16 v[186:187], v145 offset:0x600
	ds_read_b64_tr_b16 v[188:189], v145 offset:0xe00
	ds_read_b64_tr_b16 v[240:241], v145 offset:0x1600
	ds_read_b64_tr_b16 v[242:243], v145 offset:0x1e00
	ds_read_b64_tr_b16 v[244:245], v145 offset:0x2600
	ds_read_b64_tr_b16 v[246:247], v145 offset:0x2e00
	ds_read_b64_tr_b16 v[248:249], v145 offset:0x3600
	ds_read_b64_tr_b16 v[250:251], v145 offset:0x3e00
	v_mfma_f32_32x32x16_bf16 v[16:31], v[224:227], v[194:197], v[16:31]
	v_mfma_f32_32x32x16_bf16 v[16:31], v[228:231], v[212:215], v[16:31]
	v_mfma_f32_32x32x16_bf16 v[16:31], v[232:235], v[216:219], v[16:31]
	v_mfma_f32_32x32x16_bf16 v[16:31], v[236:239], v[220:223], v[16:31]
	s_waitcnt lgkmcnt(0)
; #define SBAR() __builtin_amdgcn_sched_barrier(0)
; #define BLK_Y(C0, C1, mnC, alC, t) do { if constexpr (SH) pv_d0(o, VBUF((t) & 3), pa0, pa1, pa2, pa3); else pv_d0_pipe<true>(o, VBUF((t) & 3), pa0, pa1, pa2, pa3, vfa); partialSM<SH>(C0, C1, m_reg, mnC, alC); RESC(alC); } while (0)
; template <bool SH> __device__ __forceinline__ void attn_unit(bf16_t* __restrict__ proj, int tok0, int kv0, int seq, int h, float lam, float oscale, const float* __restrict__ subg, char* lds, bool dry) {
;     ...
;     BLK_Y(pB0, pB1, mnB, alB, NT - 2);
;     finishSM<SH>(pB0, pB1, alB, l_reg, pa0, pa1, pa2, pa3); SBAR();
;     if constexpr (SH) pv_d0(o, VBUF((NT - 1) & 3), pa0, pa1, pa2, pa3); else pv_d0_pipe<false>(o, VBUF((NT - 1) & 3), pa0, pa1, pa2, pa3, vfa);
	v_exp_f32_e32 v149, v64
	v_exp_f32_e32 v151, v65
	v_exp_f32_e32 v153, v66
	v_exp_f32_e32 v155, v67
	v_mov_b32_e32 v161, v253
	v_exp_f32_e32 v157, v68
	v_pk_add_f32 v[64:65], v[148:149], v[160:161]
	v_mfma_f32_32x32x16_bf16 v[0:15], v[224:227], v[186:189], v[0:15]
	v_exp_f32_e32 v159, v69
	v_pk_add_f32 v[64:65], v[150:151], v[64:65]
	v_exp_f32_e32 v163, v70
	v_pk_add_f32 v[64:65], v[152:153], v[64:65]
	v_exp_f32_e32 v169, v71
	v_pk_add_f32 v[64:65], v[154:155], v[64:65]
	v_exp_f32_e32 v165, v72
	v_pk_add_f32 v[64:65], v[156:157], v[64:65]
	v_exp_f32_e32 v167, v73
	v_pk_add_f32 v[64:65], v[158:159], v[64:65]
	v_exp_f32_e32 v171, v74
	v_pk_add_f32 v[64:65], v[162:163], v[64:65]
	v_exp_f32_e32 v173, v75
	v_pk_add_f32 v[64:65], v[168:169], v[64:65]
	v_exp_f32_e32 v175, v76
	v_pk_add_f32 v[64:65], v[164:165], v[64:65]
	v_mfma_f32_32x32x16_bf16 v[0:15], v[228:231], v[240:243], v[0:15]
	v_exp_f32_e32 v177, v77
	v_pk_add_f32 v[64:65], v[166:167], v[64:65]
	v_exp_f32_e32 v127, v78
	v_pk_add_f32 v[64:65], v[170:171], v[64:65]
	v_exp_f32_e32 v147, v79
	v_pk_add_f32 v[64:65], v[172:173], v[64:65]
	v_exp_f32_e32 v97, v80
	v_pk_add_f32 v[64:65], v[174:175], v[64:65]
	v_exp_f32_e32 v99, v81
	v_pk_add_f32 v[64:65], v[176:177], v[64:65]
	v_exp_f32_e32 v113, v82
	v_pk_add_f32 v[64:65], v[126:127], v[64:65]
	v_exp_f32_e32 v101, v83
	v_pk_add_f32 v[64:65], v[146:147], v[64:65]
	v_exp_f32_e32 v115, v84
	v_pk_add_f32 v[64:65], v[96:97], v[64:65]
	v_mfma_f32_32x32x16_bf16 v[0:15], v[232:235], v[244:247], v[0:15]
	v_exp_f32_e32 v103, v85
	v_pk_add_f32 v[64:65], v[98:99], v[64:65]
	v_exp_f32_e32 v117, v86
	v_pk_add_f32 v[64:65], v[112:113], v[64:65]
	v_exp_f32_e32 v119, v87
	v_pk_add_f32 v[64:65], v[100:101], v[64:65]
	v_exp_f32_e32 v105, v88
	v_pk_add_f32 v[64:65], v[114:115], v[64:65]
	v_exp_f32_e32 v107, v89
	v_pk_add_f32 v[64:65], v[102:103], v[64:65]
	v_exp_f32_e32 v121, v90
	v_pk_add_f32 v[64:65], v[116:117], v[64:65]
	v_exp_f32_e32 v109, v91
	v_pk_add_f32 v[64:65], v[118:119], v[64:65]
	v_exp_f32_e32 v123, v92
	v_pk_add_f32 v[64:65], v[104:105], v[64:65]
	v_mfma_f32_32x32x16_bf16 v[0:15], v[236:239], v[248:251], v[0:15]
	v_exp_f32_e32 v111, v93
	v_pk_add_f32 v[64:65], v[106:107], v[64:65]
	v_exp_f32_e32 v125, v94
	v_pk_add_f32 v[64:65], v[120:121], v[64:65]
	v_exp_f32_e32 v145, v95
	v_pk_add_f32 v[64:65], v[108:109], v[64:65]
	v_cvt_pk_bf16_f32 v66, v157, v159
	v_pk_add_f32 v[64:65], v[122:123], v[64:65]
	v_cvt_pk_bf16_f32 v67, v163, v169
	v_pk_add_f32 v[64:65], v[110:111], v[64:65]
	v_cvt_pk_bf16_f32 v68, v165, v167
	v_pk_add_f32 v[64:65], v[124:125], v[64:65]
	v_cvt_pk_bf16_f32 v69, v171, v173
	v_pk_add_f32 v[64:65], v[144:145], v[64:65]
	v_cvt_pk_bf16_f32 v70, v175, v177
	v_add_f32_e32 v82, v64, v65
	v_cvt_pk_bf16_f32 v64, v149, v151
	v_cvt_pk_bf16_f32 v65, v153, v155
	v_cvt_pk_bf16_f32 v71, v127, v147
	v_cvt_pk_bf16_f32 v72, v97, v99
	v_cvt_pk_bf16_f32 v73, v113, v101
	v_cvt_pk_bf16_f32 v74, v115, v103
	v_cvt_pk_bf16_f32 v75, v117, v119
	v_cvt_pk_bf16_f32 v76, v105, v107
	v_cvt_pk_bf16_f32 v77, v121, v109
	v_cvt_pk_bf16_f32 v78, v123, v111
	v_cvt_pk_bf16_f32 v79, v125, v145
	v_add_u32_e32 v80, s8, v206
	ds_read_b64_tr_b16 v[84:85], v80 offset:0
	ds_read_b64_tr_b16 v[86:87], v80 offset:0x800
	ds_read_b64_tr_b16 v[88:89], v80 offset:0x1000
	ds_read_b64_tr_b16 v[90:91], v80 offset:0x1800
	ds_read_b64_tr_b16 v[92:93], v80 offset:0x2000
	ds_read_b64_tr_b16 v[94:95], v80 offset:0x2800
	ds_read_b64_tr_b16 v[96:97], v80 offset:0x3000
	ds_read_b64_tr_b16 v[98:99], v80 offset:0x3800
	s_waitcnt lgkmcnt(0)
	ds_read_b64_tr_b16 v[100:101], v80 offset:0x200
	ds_read_b64_tr_b16 v[102:103], v80 offset:0xa00
	ds_read_b64_tr_b16 v[104:105], v80 offset:0x1200
	ds_read_b64_tr_b16 v[106:107], v80 offset:0x1a00
	ds_read_b64_tr_b16 v[108:109], v80 offset:0x2200
	ds_read_b64_tr_b16 v[110:111], v80 offset:0x2a00
	ds_read_b64_tr_b16 v[112:113], v80 offset:0x3200
	ds_read_b64_tr_b16 v[114:115], v80 offset:0x3a00
	s_nop 0
	v_mfma_f32_32x32x16_bf16 v[48:63], v[64:67], v[84:87], v[48:63]
	v_mfma_f32_32x32x16_bf16 v[48:63], v[68:71], v[88:91], v[48:63]
	v_mfma_f32_32x32x16_bf16 v[48:63], v[72:75], v[92:95], v[48:63]
	v_mfma_f32_32x32x16_bf16 v[48:63], v[76:79], v[96:99], v[48:63]
	s_waitcnt lgkmcnt(0)
	ds_read_b64_tr_b16 v[84:85], v80 offset:0x400
	ds_read_b64_tr_b16 v[86:87], v80 offset:0xc00
	ds_read_b64_tr_b16 v[88:89], v80 offset:0x1400
	ds_read_b64_tr_b16 v[90:91], v80 offset:0x1c00
	ds_read_b64_tr_b16 v[92:93], v80 offset:0x2400
	ds_read_b64_tr_b16 v[94:95], v80 offset:0x2c00
	ds_read_b64_tr_b16 v[96:97], v80 offset:0x3400
	ds_read_b64_tr_b16 v[98:99], v80 offset:0x3c00
	v_mfma_f32_32x32x16_bf16 v[32:47], v[64:67], v[100:103], v[32:47]
	v_mfma_f32_32x32x16_bf16 v[32:47], v[68:71], v[104:107], v[32:47]
	v_mfma_f32_32x32x16_bf16 v[32:47], v[72:75], v[108:111], v[32:47]
	v_mfma_f32_32x32x16_bf16 v[32:47], v[76:79], v[112:115], v[32:47]
	s_waitcnt lgkmcnt(0)
	ds_read_b64_tr_b16 v[100:101], v80 offset:0x600
	ds_read_b64_tr_b16 v[102:103], v80 offset:0xe00
	ds_read_b64_tr_b16 v[104:105], v80 offset:0x1600
	ds_read_b64_tr_b16 v[106:107], v80 offset:0x1e00
	ds_read_b64_tr_b16 v[108:109], v80 offset:0x2600
	ds_read_b64_tr_b16 v[110:111], v80 offset:0x2e00
	ds_read_b64_tr_b16 v[112:113], v80 offset:0x3600
	ds_read_b64_tr_b16 v[114:115], v80 offset:0x3e00
	v_mfma_f32_32x32x16_bf16 v[16:31], v[64:67], v[84:87], v[16:31]
	v_mfma_f32_32x32x16_bf16 v[16:31], v[68:71], v[88:91], v[16:31]
	v_mfma_f32_32x32x16_bf16 v[16:31], v[72:75], v[92:95], v[16:31]
	v_mfma_f32_32x32x16_bf16 v[16:31], v[76:79], v[96:99], v[16:31]
	s_waitcnt lgkmcnt(0)
	v_mfma_f32_32x32x16_bf16 v[0:15], v[64:67], v[100:103], v[0:15]
	s_mov_b64 s[12:13], 0
	v_mfma_f32_32x32x16_bf16 v[0:15], v[68:71], v[104:107], v[0:15]
	v_mfma_f32_32x32x16_bf16 v[0:15], v[72:75], v[108:111], v[0:15]
	v_mfma_f32_32x32x16_bf16 v[0:15], v[76:79], v[112:115], v[0:15]
